# K-loops: removed the duplicate s_waitcnt lgkmcnt(0) after each barrier (the one before the barrier already drains LDS), 4 per iteration on the pre-MFMA path
# speedup vs baseline: 1.0052x; 1.0052x over previous
; #define PG8_STAGE(bufoff, gbase, voff) do { _Pragma("unroll") for (int _i = 0; _i < 2; ++_i) \
;         __builtin_amdgcn_global_load_lds((const unsigned*)((const char*)(gbase) + (voff)[_i]), (PG8_LAS unsigned*)(lds + (bufoff) + ldsw + _i * 8192), 16, 0, 0); } while (0)
; #define PG8_LDA(dst, b, h) do { _Pragma("unroll") for (int m = 0; m < 4; ++m) _Pragma("unroll") for (int k = 0; k < 2; ++k) dst[m][k] = *(const PG8_LAS bf16x8*)(lds + PG8_SA(b, h) + aoff + m * 2048 + k * 1024); } while (0)
; #define PG8_LDB(dst, b, h) do { _Pragma("unroll") for (int n = 0; n < 2; ++n) _Pragma("unroll") for (int k = 0; k < 2; ++k) dst[n][k] = *(const PG8_LAS bf16x8*)(lds + PG8_SB(b, h) + boff + n * 2048 + k * 1024); } while (0)
; #define PG8_MMA(ai, bj, At, Bt) do { __builtin_amdgcn_s_setprio(1); _Pragma("unroll") for (int m = 0; m < 4; ++m) _Pragma("unroll") for (int n = 0; n < 2; ++n) _Pragma("unroll") for (int k = 0; k < 2; ++k) \
;         acc[ai][bj][m][n] = __builtin_amdgcn_mfma_f32_16x16x32_bf16(Bt[n][k], At[m][k], acc[ai][bj][m][n], 0, 0, 0); __builtin_amdgcn_s_setprio(0); } while (0)
; #define PG8_WAIT_V(n) asm volatile("s_waitcnt vmcnt(" #n ")" ::: "memory")
; #define PG8_WAIT_L(n) asm volatile("s_waitcnt lgkmcnt(" #n ")" ::: "memory")
; #define PG8_BAR __builtin_amdgcn_s_barrier()
; template <class Epi, class Sched, bool ALIGN_EPI = true>
; __device__ __forceinline__ void gemm_phase(PG8_LAS unsigned char* lds, const Gemm g, const Sched& S, const Epi& E, const int tid) {
;     ...
;             const bool last = (t == nt - 2);
;             const char* a1 = cA + (size_t)(t + 1) * kstep;
;             const char* a2 = last ? nA : cA + (size_t)(t + 2) * kstep; const char* b2 = last ? nB : cB + (size_t)(t + 2) * kstep;
;             const char* a3 = a2 + kstep; const char* b3 = b2 + kstep;
;             if (last && has_next) S.a_ready(nxt);
;             PG8_LDB(B0, 0, 0); PG8_LDB(B1, 0, 1); PG8_SCHED; PG8_LDA(At, 0, 0); PG8_STAGE(PG8_SA(1, 1), a1 + hstepA, voffA);
;             PG8_WAIT_V(8); PG8_WAIT_L(0); PG8_BAR; PG8_MMA(0, 0, At, B0); PG8_MMA(0, 1, At, B1); PG8_BAR; PG8_SCHED;
;             PG8_LDA(At, 0, 1); PG8_STAGE(PG8_SB(0, 0), b2, voffB); PG8_STAGE(PG8_SB(0, 1), b2 + hstepB, voffB); PG8_STAGE(PG8_SA(0, 0), a2, voffA);
;             PG8_WAIT_V(8); PG8_WAIT_L(0); PG8_BAR; PG8_MMA(1, 0, At, B0); PG8_MMA(1, 1, At, B1); PG8_BAR; PG8_SCHED;
.LBB0_426:
	s_add_u32 s15, s12, 0xfff80080
	s_addc_u32 s16, s13, -1
	s_add_i32 s17, 0, 0x10000
	s_cmp_eq_u32 s53, 4
	s_cselect_b32 s63, s1, s16
	s_cselect_b32 s62, s5, s15
	s_cselect_b32 s23, s8, s21
	s_cselect_b32 s22, s9, s20
	s_add_i32 s15, 0, 0x14000
	v_add_u32_e32 v72, s17, v251
	v_add_u32_e32 v136, s15, v251
	ds_read_b128 v[60:63], v72
	ds_read_b128 v[64:67], v72 offset:1024
	ds_read_b128 v[68:71], v72 offset:2048
	ds_read_b128 v[72:75], v72 offset:3072
	ds_read_b128 v[100:103], v136
	ds_read_b128 v[112:115], v136 offset:1024
	ds_read_b128 v[116:119], v136 offset:2048
	ds_read_b128 v[136:139], v136 offset:3072
	s_add_i32 m0, s11, 0xc000
	ds_read_b128 v[140:143], v252
	ds_read_b128 v[152:155], v252 offset:1024
	ds_read_b128 v[156:159], v252 offset:2048
	ds_read_b128 v[168:171], v252 offset:3072
	ds_read_b128 v[172:175], v252 offset:4096
	ds_read_b128 v[184:187], v252 offset:5120
	ds_read_b128 v[188:191], v252 offset:6144
	ds_read_b128 v[192:195], v252 offset:7168
	global_load_lds_dwordx4 v216, s[12:13]
	s_add_i32 m0, s11, 0xe000
	s_nop 0
	global_load_lds_dwordx4 v218, s[12:13]
	s_waitcnt vmcnt(8)
	s_waitcnt lgkmcnt(0)
	s_barrier
	v_mfma_f32_16x16x32_bf16 v[180:183], v[60:63], v[140:143], v[180:183]
	v_mfma_f32_16x16x32_bf16 v[180:183], v[64:67], v[152:155], v[180:183]
	v_mfma_f32_16x16x32_bf16 v[176:179], v[72:75], v[152:155], v[176:179]
	v_mfma_f32_16x16x32_bf16 v[176:179], v[68:71], v[140:143], v[176:179]
	v_mfma_f32_16x16x32_bf16 v[144:147], v[68:71], v[156:159], v[144:147]
	v_mfma_f32_16x16x32_bf16 v[144:147], v[72:75], v[168:171], v[144:147]
	v_mfma_f32_16x16x32_bf16 v[148:151], v[64:67], v[168:171], v[148:151]
	v_mfma_f32_16x16x32_bf16 v[148:151], v[60:63], v[156:159], v[148:151]
	v_mfma_f32_16x16x32_bf16 v[124:127], v[60:63], v[172:175], v[124:127]
	v_mfma_f32_16x16x32_bf16 v[124:127], v[64:67], v[184:187], v[124:127]
	v_mfma_f32_16x16x32_bf16 v[120:123], v[72:75], v[184:187], v[120:123]
	v_mfma_f32_16x16x32_bf16 v[120:123], v[68:71], v[172:175], v[120:123]
	v_mfma_f32_16x16x32_bf16 v[92:95], v[68:71], v[188:191], v[92:95]
	v_mfma_f32_16x16x32_bf16 v[92:95], v[72:75], v[192:195], v[92:95]
	v_mfma_f32_16x16x32_bf16 v[96:99], v[64:67], v[192:195], v[96:99]
	v_mfma_f32_16x16x32_bf16 v[96:99], v[60:63], v[188:191], v[96:99]
	v_mfma_f32_16x16x32_bf16 v[164:167], v[100:103], v[140:143], v[164:167]
	v_mfma_f32_16x16x32_bf16 v[164:167], v[112:115], v[152:155], v[164:167]
	v_mfma_f32_16x16x32_bf16 v[132:135], v[112:115], v[168:171], v[132:135]
	v_mfma_f32_16x16x32_bf16 v[132:135], v[100:103], v[156:159], v[132:135]
	v_mfma_f32_16x16x32_bf16 v[128:131], v[116:119], v[156:159], v[128:131]
	v_mfma_f32_16x16x32_bf16 v[128:131], v[136:139], v[168:171], v[128:131]
	v_mfma_f32_16x16x32_bf16 v[104:107], v[136:139], v[184:187], v[104:107]
	v_mfma_f32_16x16x32_bf16 v[104:107], v[116:119], v[172:175], v[104:107]
	v_mfma_f32_16x16x32_bf16 v[108:111], v[100:103], v[172:175], v[108:111]
	v_mfma_f32_16x16x32_bf16 v[108:111], v[112:115], v[184:187], v[108:111]
	v_mfma_f32_16x16x32_bf16 v[88:91], v[112:115], v[192:195], v[88:91]
	v_mfma_f32_16x16x32_bf16 v[88:91], v[100:103], v[188:191], v[88:91]
	v_mfma_f32_16x16x32_bf16 v[84:87], v[116:119], v[188:191], v[84:87]
	v_mfma_f32_16x16x32_bf16 v[84:87], v[136:139], v[192:195], v[84:87]
	v_mfma_f32_16x16x32_bf16 v[140:143], v[116:119], v[140:143], v[160:163]
	v_mfma_f32_16x16x32_bf16 v[140:143], v[136:139], v[152:155], v[140:143]
	s_barrier
	s_add_i32 s16, s17, s67
	s_mov_b32 m0, s16
	ds_read_b128 v[152:155], v252 offset:16384
	ds_read_b128 v[156:159], v252 offset:17408
	ds_read_b128 v[160:163], v252 offset:18432
	ds_read_b128 v[168:171], v252 offset:19456
	ds_read_b128 v[172:175], v252 offset:20480
	ds_read_b128 v[184:187], v252 offset:21504
	ds_read_b128 v[188:191], v252 offset:22528
	ds_read_b128 v[192:195], v252 offset:23552
	global_load_lds_dwordx4 v2, s[22:23]
	s_add_i32 m0, s16, 0x2000
	s_add_u32 s78, s22, 0x20000
	s_addc_u32 s79, s23, 0
	s_add_i32 s15, s15, s67
	global_load_lds_dwordx4 v210, s[22:23]
	s_mov_b32 m0, s15
	s_nop 0
	global_load_lds_dwordx4 v2, s[78:79]
	s_add_i32 m0, s15, 0x2000
	s_nop 0
	global_load_lds_dwordx4 v210, s[78:79]
	s_mov_b32 m0, s11
	s_nop 0
	global_load_lds_dwordx4 v214, s[62:63]
	s_mov_b32 m0, s68
	s_nop 0
	global_load_lds_dwordx4 v212, s[62:63]
	s_waitcnt vmcnt(8)
	s_waitcnt lgkmcnt(0)
	s_barrier
	v_mfma_f32_16x16x32_bf16 v[80:83], v[60:63], v[152:155], v[80:83]
	v_mfma_f32_16x16x32_bf16 v[80:83], v[64:67], v[156:159], v[80:83]
	v_mfma_f32_16x16x32_bf16 v[76:79], v[72:75], v[156:159], v[76:79]
	v_mfma_f32_16x16x32_bf16 v[76:79], v[68:71], v[152:155], v[76:79]
	v_mfma_f32_16x16x32_bf16 v[44:47], v[68:71], v[160:163], v[44:47]
	v_mfma_f32_16x16x32_bf16 v[44:47], v[72:75], v[168:171], v[44:47]
	v_mfma_f32_16x16x32_bf16 v[48:51], v[64:67], v[168:171], v[48:51]
	v_mfma_f32_16x16x32_bf16 v[48:51], v[60:63], v[160:163], v[48:51]
	v_mfma_f32_16x16x32_bf16 v[32:35], v[60:63], v[172:175], v[32:35]
	v_mfma_f32_16x16x32_bf16 v[32:35], v[64:67], v[184:187], v[32:35]
	v_mfma_f32_16x16x32_bf16 v[28:31], v[72:75], v[184:187], v[28:31]
	v_mfma_f32_16x16x32_bf16 v[28:31], v[68:71], v[172:175], v[28:31]
	v_mfma_f32_16x16x32_bf16 v[12:15], v[68:71], v[188:191], v[12:15]
	v_mfma_f32_16x16x32_bf16 v[12:15], v[72:75], v[192:195], v[12:15]
	v_mfma_f32_16x16x32_bf16 v[16:19], v[64:67], v[192:195], v[16:19]
	v_mfma_f32_16x16x32_bf16 v[16:19], v[60:63], v[188:191], v[16:19]
	v_mfma_f32_16x16x32_bf16 v[56:59], v[100:103], v[152:155], v[56:59]
	v_mfma_f32_16x16x32_bf16 v[56:59], v[112:115], v[156:159], v[56:59]
	v_mfma_f32_16x16x32_bf16 v[52:55], v[136:139], v[156:159], v[52:55]
	v_mfma_f32_16x16x32_bf16 v[52:55], v[116:119], v[152:155], v[52:55]
	v_mfma_f32_16x16x32_bf16 v[36:39], v[116:119], v[160:163], v[36:39]
	v_mfma_f32_16x16x32_bf16 v[36:39], v[136:139], v[168:171], v[36:39]
	v_mfma_f32_16x16x32_bf16 v[40:43], v[112:115], v[168:171], v[40:43]
	v_mfma_f32_16x16x32_bf16 v[40:43], v[100:103], v[160:163], v[40:43]
	v_mfma_f32_16x16x32_bf16 v[24:27], v[100:103], v[172:175], v[24:27]
	v_mfma_f32_16x16x32_bf16 v[24:27], v[112:115], v[184:187], v[24:27]
	v_mfma_f32_16x16x32_bf16 v[20:23], v[136:139], v[184:187], v[20:23]
	v_mfma_f32_16x16x32_bf16 v[20:23], v[116:119], v[172:175], v[20:23]
	v_mfma_f32_16x16x32_bf16 v[4:7], v[116:119], v[188:191], v[4:7]
	v_mfma_f32_16x16x32_bf16 v[4:7], v[136:139], v[192:195], v[4:7]
	v_mfma_f32_16x16x32_bf16 v[8:11], v[112:115], v[192:195], v[8:11]
	v_mfma_f32_16x16x32_bf16 v[8:11], v[100:103], v[188:191], v[8:11]
	s_barrier
; #define PG8_STAGE(bufoff, gbase, voff) do { _Pragma("unroll") for (int _i = 0; _i < 2; ++_i) \
;         __builtin_amdgcn_global_load_lds((const unsigned*)((const char*)(gbase) + (voff)[_i]), (PG8_LAS unsigned*)(lds + (bufoff) + ldsw + _i * 8192), 16, 0, 0); } while (0)
; #define PG8_LDA(dst, b, h) do { _Pragma("unroll") for (int m = 0; m < 4; ++m) _Pragma("unroll") for (int k = 0; k < 2; ++k) dst[m][k] = *(const PG8_LAS bf16x8*)(lds + PG8_SA(b, h) + aoff + m * 2048 + k * 1024); } while (0)
; #define PG8_LDB(dst, b, h) do { _Pragma("unroll") for (int n = 0; n < 2; ++n) _Pragma("unroll") for (int k = 0; k < 2; ++k) dst[n][k] = *(const PG8_LAS bf16x8*)(lds + PG8_SB(b, h) + boff + n * 2048 + k * 1024); } while (0)
; #define PG8_MMA(ai, bj, At, Bt) do { __builtin_amdgcn_s_setprio(1); _Pragma("unroll") for (int m = 0; m < 4; ++m) _Pragma("unroll") for (int n = 0; n < 2; ++n) _Pragma("unroll") for (int k = 0; k < 2; ++k) \
;         acc[ai][bj][m][n] = __builtin_amdgcn_mfma_f32_16x16x32_bf16(Bt[n][k], At[m][k], acc[ai][bj][m][n], 0, 0, 0); __builtin_amdgcn_s_setprio(0); } while (0)
; #define PG8_WAIT_V(n) asm volatile("s_waitcnt vmcnt(" #n ")" ::: "memory")
; #define PG8_WAIT_L(n) asm volatile("s_waitcnt lgkmcnt(" #n ")" ::: "memory")
; #define PG8_BAR __builtin_amdgcn_s_barrier()
; #define PG8_SCHED __builtin_amdgcn_sched_barrier(0)
; template <class Epi, class Sched, bool ALIGN_EPI = true>
; __device__ __forceinline__ void gemm_phase(PG8_LAS unsigned char* lds, const Gemm g, const Sched& S, const Epi& E, const int tid) {
;     ...
;             PG8_LDB(B0, 1, 0); PG8_LDB(B1, 1, 1); PG8_SCHED; PG8_LDA(At, 1, 0); PG8_STAGE(PG8_SA(0, 1), a2 + hstepA, voffA);
;             PG8_WAIT_V(8); PG8_WAIT_L(0); PG8_BAR; PG8_MMA(0, 0, At, B0); PG8_MMA(0, 1, At, B1); PG8_BAR; PG8_SCHED;
;             PG8_LDA(At, 1, 1); PG8_STAGE(PG8_SB(1, 0), b3, voffB); PG8_STAGE(PG8_SB(1, 1), b3 + hstepB, voffB); PG8_STAGE(PG8_SA(1, 0), a3, voffA);
;             PG8_WAIT_V(8); PG8_WAIT_L(0); PG8_BAR; PG8_MMA(1, 0, At, B0); PG8_MMA(1, 1, At, B1); PG8_BAR; PG8_SCHED;
;         }
	s_add_i32 s15, 0, 0x18000
	s_add_i32 s16, 0, 0x1c000
	v_add_u32_e32 v72, s15, v251
	v_add_u32_e32 v136, s16, v251
	ds_read_b128 v[60:63], v72
	ds_read_b128 v[64:67], v72 offset:1024
	ds_read_b128 v[68:71], v72 offset:2048
	ds_read_b128 v[72:75], v72 offset:3072
	ds_read_b128 v[100:103], v136
	ds_read_b128 v[112:115], v136 offset:1024
	ds_read_b128 v[116:119], v136 offset:2048
	ds_read_b128 v[136:139], v136 offset:3072
	s_add_u32 s62, s62, 0x80000
	s_addc_u32 s63, s63, 0
	s_mov_b32 m0, s69
	ds_read_b128 v[152:155], v252 offset:32768
	ds_read_b128 v[156:159], v252 offset:33792
	ds_read_b128 v[168:171], v252 offset:34816
	ds_read_b128 v[172:175], v252 offset:35840
	ds_read_b128 v[184:187], v252 offset:36864
	ds_read_b128 v[188:191], v252 offset:37888
	ds_read_b128 v[192:195], v252 offset:38912
	ds_read_b128 v[196:199], v252 offset:39936
	global_load_lds_dwordx4 v214, s[62:63]
	s_mov_b32 m0, s70
	s_nop 0
	global_load_lds_dwordx4 v212, s[62:63]
	s_waitcnt vmcnt(8)
	s_waitcnt lgkmcnt(0)
	s_barrier
	v_mfma_f32_16x16x32_bf16 v[160:163], v[60:63], v[152:155], v[180:183]
	v_mfma_f32_16x16x32_bf16 v[180:183], v[64:67], v[156:159], v[160:163]
	v_mfma_f32_16x16x32_bf16 v[148:151], v[64:67], v[172:175], v[148:151]
	v_mfma_f32_16x16x32_bf16 v[148:151], v[60:63], v[168:171], v[148:151]
	v_mfma_f32_16x16x32_bf16 v[144:147], v[68:71], v[168:171], v[144:147]
	v_mfma_f32_16x16x32_bf16 v[144:147], v[72:75], v[172:175], v[144:147]
	v_mfma_f32_16x16x32_bf16 v[120:123], v[72:75], v[188:191], v[120:123]
	v_mfma_f32_16x16x32_bf16 v[120:123], v[68:71], v[184:187], v[120:123]
	v_mfma_f32_16x16x32_bf16 v[160:163], v[68:71], v[152:155], v[176:179]
	v_mfma_f32_16x16x32_bf16 v[176:179], v[72:75], v[156:159], v[160:163]
	v_mfma_f32_16x16x32_bf16 v[92:95], v[72:75], v[196:199], v[92:95]
	v_mfma_f32_16x16x32_bf16 v[92:95], v[68:71], v[192:195], v[92:95]
	v_mfma_f32_16x16x32_bf16 v[96:99], v[60:63], v[192:195], v[96:99]
	v_mfma_f32_16x16x32_bf16 v[96:99], v[64:67], v[196:199], v[96:99]
	v_mfma_f32_16x16x32_bf16 v[124:127], v[64:67], v[188:191], v[124:127]
	v_mfma_f32_16x16x32_bf16 v[124:127], v[60:63], v[184:187], v[124:127]
	v_mfma_f32_16x16x32_bf16 v[160:163], v[100:103], v[152:155], v[164:167]
	v_mfma_f32_16x16x32_bf16 v[164:167], v[112:115], v[156:159], v[160:163]
	v_mfma_f32_16x16x32_bf16 v[132:135], v[112:115], v[172:175], v[132:135]
	v_mfma_f32_16x16x32_bf16 v[132:135], v[100:103], v[168:171], v[132:135]
	v_mfma_f32_16x16x32_bf16 v[128:131], v[116:119], v[168:171], v[128:131]
	v_mfma_f32_16x16x32_bf16 v[128:131], v[136:139], v[172:175], v[128:131]
	v_mfma_f32_16x16x32_bf16 v[104:107], v[136:139], v[188:191], v[104:107]
	v_mfma_f32_16x16x32_bf16 v[104:107], v[116:119], v[184:187], v[104:107]
	v_mfma_f32_16x16x32_bf16 v[140:143], v[116:119], v[152:155], v[140:143]
	v_mfma_f32_16x16x32_bf16 v[160:163], v[136:139], v[156:159], v[140:143]
	v_mfma_f32_16x16x32_bf16 v[84:87], v[136:139], v[196:199], v[84:87]
	v_mfma_f32_16x16x32_bf16 v[84:87], v[116:119], v[192:195], v[84:87]
	v_mfma_f32_16x16x32_bf16 v[88:91], v[100:103], v[192:195], v[88:91]
	v_mfma_f32_16x16x32_bf16 v[88:91], v[112:115], v[196:199], v[88:91]
	v_mfma_f32_16x16x32_bf16 v[108:111], v[112:115], v[188:191], v[108:111]
	v_mfma_f32_16x16x32_bf16 v[108:111], v[100:103], v[184:187], v[108:111]
	s_barrier
	s_add_i32 s15, s15, s67
	s_mov_b32 m0, s15
	ds_read_b128 v[140:143], v252 offset:49152
	ds_read_b128 v[152:155], v252 offset:50176
	ds_read_b128 v[156:159], v252 offset:51200
	ds_read_b128 v[168:171], v252 offset:52224
	ds_read_b128 v[172:175], v252 offset:53248
	ds_read_b128 v[184:187], v252 offset:54272
	ds_read_b128 v[188:191], v252 offset:55296
	ds_read_b128 v[192:195], v252 offset:56320
	s_add_u32 s98, s22, 0x80
	s_addc_u32 s99, s23, 0
	global_load_lds_dwordx4 v2, s[98:99]
	s_add_i32 m0, s15, 0x2000
	s_add_u32 s22, s22, 0x20080
	s_addc_u32 s23, s23, 0
	s_add_i32 s15, s16, s67
	global_load_lds_dwordx4 v210, s[98:99]
	s_mov_b32 m0, s15
	s_nop 0
	global_load_lds_dwordx4 v2, s[22:23]
	s_add_i32 m0, s15, 0x2000
	s_nop 0
	global_load_lds_dwordx4 v210, s[22:23]
	s_mov_b32 m0, s75
	s_nop 0
	s_add_u32 s98, s62, 0xfff80080
	s_addc_u32 s99, s63, -1
	global_load_lds_dwordx4 v214, s[98:99]
	s_mov_b32 m0, s76
	s_nop 0
	global_load_lds_dwordx4 v212, s[98:99]
	s_waitcnt vmcnt(8)
	s_waitcnt lgkmcnt(0)
	s_barrier
	v_mfma_f32_16x16x32_bf16 v[80:83], v[60:63], v[140:143], v[80:83]
	v_mfma_f32_16x16x32_bf16 v[80:83], v[64:67], v[152:155], v[80:83]
	v_mfma_f32_16x16x32_bf16 v[76:79], v[72:75], v[152:155], v[76:79]
	v_mfma_f32_16x16x32_bf16 v[76:79], v[68:71], v[140:143], v[76:79]
	v_mfma_f32_16x16x32_bf16 v[44:47], v[68:71], v[156:159], v[44:47]
	v_mfma_f32_16x16x32_bf16 v[44:47], v[72:75], v[168:171], v[44:47]
	v_mfma_f32_16x16x32_bf16 v[48:51], v[64:67], v[168:171], v[48:51]
	v_mfma_f32_16x16x32_bf16 v[48:51], v[60:63], v[156:159], v[48:51]
	v_mfma_f32_16x16x32_bf16 v[32:35], v[60:63], v[172:175], v[32:35]
	v_mfma_f32_16x16x32_bf16 v[32:35], v[64:67], v[184:187], v[32:35]
	v_mfma_f32_16x16x32_bf16 v[28:31], v[72:75], v[184:187], v[28:31]
	v_mfma_f32_16x16x32_bf16 v[28:31], v[68:71], v[172:175], v[28:31]
	v_mfma_f32_16x16x32_bf16 v[12:15], v[68:71], v[188:191], v[12:15]
	v_mfma_f32_16x16x32_bf16 v[12:15], v[72:75], v[192:195], v[12:15]
	v_mfma_f32_16x16x32_bf16 v[16:19], v[64:67], v[192:195], v[16:19]
	v_mfma_f32_16x16x32_bf16 v[16:19], v[60:63], v[188:191], v[16:19]
	v_mfma_f32_16x16x32_bf16 v[56:59], v[100:103], v[140:143], v[56:59]
	v_mfma_f32_16x16x32_bf16 v[56:59], v[112:115], v[152:155], v[56:59]
	v_mfma_f32_16x16x32_bf16 v[52:55], v[136:139], v[152:155], v[52:55]
	v_mfma_f32_16x16x32_bf16 v[52:55], v[116:119], v[140:143], v[52:55]
	v_mfma_f32_16x16x32_bf16 v[36:39], v[116:119], v[156:159], v[36:39]
	v_mfma_f32_16x16x32_bf16 v[36:39], v[136:139], v[168:171], v[36:39]
	v_mfma_f32_16x16x32_bf16 v[40:43], v[112:115], v[168:171], v[40:43]
	v_mfma_f32_16x16x32_bf16 v[40:43], v[100:103], v[156:159], v[40:43]
	v_mfma_f32_16x16x32_bf16 v[24:27], v[100:103], v[172:175], v[24:27]
	v_mfma_f32_16x16x32_bf16 v[24:27], v[112:115], v[184:187], v[24:27]
	v_mfma_f32_16x16x32_bf16 v[20:23], v[136:139], v[184:187], v[20:23]
	v_mfma_f32_16x16x32_bf16 v[20:23], v[116:119], v[172:175], v[20:23]
	v_mfma_f32_16x16x32_bf16 v[4:7], v[116:119], v[188:191], v[4:7]
	v_mfma_f32_16x16x32_bf16 v[4:7], v[136:139], v[192:195], v[4:7]
	v_mfma_f32_16x16x32_bf16 v[8:11], v[112:115], v[192:195], v[8:11]
	v_mfma_f32_16x16x32_bf16 v[8:11], v[100:103], v[188:191], v[8:11]
	s_barrier
	s_add_i32 s53, s53, 2
	s_add_u32 s12, s12, 0x100
	s_addc_u32 s13, s13, 0
	s_add_u32 s20, s20, 0x100
	s_addc_u32 s21, s21, 0
	s_cmp_gt_u32 s53, 5
	s_cbranch_scc0 .LBB0_426
	s_and_b64 vcc, exec, s[48:49]
	s_cbranch_vccz .LBB0_429
	s_barrier

; #define PG8_STAGE(bufoff, gbase, voff) do { _Pragma("unroll") for (int _i = 0; _i < 2; ++_i) \
;         __builtin_amdgcn_global_load_lds((const unsigned*)((const char*)(gbase) + (voff)[_i]), (PG8_LAS unsigned*)(lds + (bufoff) + ldsw + _i * 8192), 16, 0, 0); } while (0)
; #define PG8_LDA(dst, b, h) do { _Pragma("unroll") for (int m = 0; m < 4; ++m) _Pragma("unroll") for (int k = 0; k < 2; ++k) dst[m][k] = *(const PG8_LAS bf16x8*)(lds + PG8_SA(b, h) + aoff + m * 2048 + k * 1024); } while (0)
; #define PG8_LDB(dst, b, h) do { _Pragma("unroll") for (int n = 0; n < 2; ++n) _Pragma("unroll") for (int k = 0; k < 2; ++k) dst[n][k] = *(const PG8_LAS bf16x8*)(lds + PG8_SB(b, h) + boff + n * 2048 + k * 1024); } while (0)
; #define PG8_MMA(ai, bj, At, Bt) do { __builtin_amdgcn_s_setprio(1); _Pragma("unroll") for (int m = 0; m < 4; ++m) _Pragma("unroll") for (int n = 0; n < 2; ++n) _Pragma("unroll") for (int k = 0; k < 2; ++k) \
;         acc[ai][bj][m][n] = __builtin_amdgcn_mfma_f32_16x16x32_bf16(Bt[n][k], At[m][k], acc[ai][bj][m][n], 0, 0, 0); __builtin_amdgcn_s_setprio(0); } while (0)
; #define PG8_WAIT_V(n) asm volatile("s_waitcnt vmcnt(" #n ")" ::: "memory")
; #define PG8_WAIT_L(n) asm volatile("s_waitcnt lgkmcnt(" #n ")" ::: "memory")
; #define PG8_BAR __builtin_amdgcn_s_barrier()
; template <class Epi, class Sched, bool ALIGN_EPI = true>
; __device__ __forceinline__ void gemm_phase(PG8_LAS unsigned char* lds, const Gemm g, const Sched& S, const Epi& E, const int tid) {
;     ...
;             const bool last = (t == nt - 2);
;             const char* a1 = cA + (size_t)(t + 1) * kstep;
;             const char* a2 = last ? nA : cA + (size_t)(t + 2) * kstep; const char* b2 = last ? nB : cB + (size_t)(t + 2) * kstep;
;             const char* a3 = a2 + kstep; const char* b3 = b2 + kstep;
;             if (last && has_next) S.a_ready(nxt);
;             PG8_LDB(B0, 0, 0); PG8_LDB(B1, 0, 1); PG8_SCHED; PG8_LDA(At, 0, 0); PG8_STAGE(PG8_SA(1, 1), a1 + hstepA, voffA);
;             PG8_WAIT_V(8); PG8_WAIT_L(0); PG8_BAR; PG8_MMA(0, 0, At, B0); PG8_MMA(0, 1, At, B1); PG8_BAR; PG8_SCHED;
;             PG8_LDA(At, 0, 1); PG8_STAGE(PG8_SB(0, 0), b2, voffB); PG8_STAGE(PG8_SB(0, 1), b2 + hstepB, voffB); PG8_STAGE(PG8_SA(0, 0), a2, voffA);
;             PG8_WAIT_V(8); PG8_WAIT_L(0); PG8_BAR; PG8_MMA(1, 0, At, B0); PG8_MMA(1, 1, At, B1); PG8_BAR; PG8_SCHED;
.LBB0_514:
	s_add_u32 s44, s42, 0xfff80080
	s_addc_u32 s45, s43, -1
	s_add_i32 s57, 0, 0x10000
	s_cmp_eq_u32 s56, 28
	s_cselect_b32 s47, s13, s45
	s_cselect_b32 s46, s52, s44
	s_cselect_b32 s45, s23, s55
	s_cselect_b32 s44, s53, s54
	s_add_i32 s60, 0, 0x14000
	v_add_u32_e32 v158, s57, v147
	v_add_u32_e32 v174, s60, v147
	ds_read_b128 v[142:145], v158
	ds_read_b128 v[150:153], v158 offset:1024
	ds_read_b128 v[154:157], v158 offset:2048
	ds_read_b128 v[158:161], v158 offset:3072
	ds_read_b128 v[162:165], v174
	ds_read_b128 v[166:169], v174 offset:1024
	ds_read_b128 v[170:173], v174 offset:2048
	ds_read_b128 v[174:177], v174 offset:3072
	s_add_i32 m0, s7, 0xc000
	ds_read_b128 v[178:181], v149
	ds_read_b128 v[182:185], v149 offset:1024
	ds_read_b128 v[186:189], v149 offset:2048
	ds_read_b128 v[190:193], v149 offset:3072
	ds_read_b128 v[194:197], v149 offset:4096
	ds_read_b128 v[198:201], v149 offset:5120
	ds_read_b128 v[202:205], v149 offset:6144
	ds_read_b128 v[210:213], v149 offset:7168
	global_load_lds_dwordx4 v138, s[42:43]
	s_add_i32 m0, s7, 0xe000
	s_nop 0
	global_load_lds_dwordx4 v140, s[42:43]
	s_waitcnt vmcnt(8)
	s_waitcnt lgkmcnt(0)
	s_barrier
	v_mfma_f32_16x16x32_bf16 v[128:131], v[142:145], v[178:181], v[128:131]
	v_mfma_f32_16x16x32_bf16 v[128:131], v[150:153], v[182:185], v[128:131]
	v_mfma_f32_16x16x32_bf16 v[124:127], v[158:161], v[182:185], v[124:127]
	v_mfma_f32_16x16x32_bf16 v[124:127], v[154:157], v[178:181], v[124:127]
	v_mfma_f32_16x16x32_bf16 v[112:115], v[154:157], v[186:189], v[112:115]
	v_mfma_f32_16x16x32_bf16 v[112:115], v[158:161], v[190:193], v[112:115]
	v_mfma_f32_16x16x32_bf16 v[120:123], v[150:153], v[190:193], v[120:123]
	v_mfma_f32_16x16x32_bf16 v[120:123], v[142:145], v[186:189], v[120:123]
	v_mfma_f32_16x16x32_bf16 v[104:107], v[142:145], v[194:197], v[104:107]
	v_mfma_f32_16x16x32_bf16 v[104:107], v[150:153], v[198:201], v[104:107]
	v_mfma_f32_16x16x32_bf16 v[96:99], v[158:161], v[198:201], v[96:99]
	v_mfma_f32_16x16x32_bf16 v[96:99], v[154:157], v[194:197], v[96:99]
	v_mfma_f32_16x16x32_bf16 v[80:83], v[154:157], v[202:205], v[80:83]
	v_mfma_f32_16x16x32_bf16 v[80:83], v[158:161], v[210:213], v[80:83]
	v_mfma_f32_16x16x32_bf16 v[88:91], v[150:153], v[210:213], v[88:91]
	v_mfma_f32_16x16x32_bf16 v[88:91], v[142:145], v[202:205], v[88:91]
	v_mfma_f32_16x16x32_bf16 v[116:119], v[162:165], v[178:181], v[116:119]
	v_mfma_f32_16x16x32_bf16 v[116:119], v[166:169], v[182:185], v[116:119]
	v_mfma_f32_16x16x32_bf16 v[108:111], v[174:177], v[182:185], v[108:111]
	v_mfma_f32_16x16x32_bf16 v[108:111], v[170:173], v[178:181], v[108:111]
	v_mfma_f32_16x16x32_bf16 v[92:95], v[170:173], v[186:189], v[92:95]
	v_mfma_f32_16x16x32_bf16 v[92:95], v[174:177], v[190:193], v[92:95]
	v_mfma_f32_16x16x32_bf16 v[100:103], v[166:169], v[190:193], v[100:103]
	v_mfma_f32_16x16x32_bf16 v[100:103], v[162:165], v[186:189], v[100:103]
	v_mfma_f32_16x16x32_bf16 v[84:87], v[162:165], v[194:197], v[84:87]
	v_mfma_f32_16x16x32_bf16 v[84:87], v[166:169], v[198:201], v[84:87]
	v_mfma_f32_16x16x32_bf16 v[76:79], v[174:177], v[198:201], v[76:79]
	v_mfma_f32_16x16x32_bf16 v[76:79], v[170:173], v[194:197], v[76:79]
	v_mfma_f32_16x16x32_bf16 v[68:71], v[170:173], v[202:205], v[68:71]
	v_mfma_f32_16x16x32_bf16 v[68:71], v[174:177], v[210:213], v[68:71]
	v_mfma_f32_16x16x32_bf16 v[72:75], v[166:169], v[210:213], v[72:75]
	v_mfma_f32_16x16x32_bf16 v[72:75], v[162:165], v[202:205], v[72:75]
	s_barrier
	s_add_i32 s57, s57, s21
	s_mov_b32 m0, s57
	ds_read_b128 v[178:181], v149 offset:16384
	ds_read_b128 v[182:185], v149 offset:17408
	ds_read_b128 v[186:189], v149 offset:18432
	ds_read_b128 v[190:193], v149 offset:19456
	ds_read_b128 v[194:197], v149 offset:20480
	ds_read_b128 v[198:201], v149 offset:21504
	ds_read_b128 v[202:205], v149 offset:22528
	ds_read_b128 v[210:213], v149 offset:23552
	global_load_lds_dwordx4 v2, s[44:45]
	s_add_i32 m0, s57, 0x2000
	s_add_u32 s58, s44, 0x80000
	s_addc_u32 s59, s45, 0
	s_add_i32 s57, s60, s21
	global_load_lds_dwordx4 v132, s[44:45]
	s_mov_b32 m0, s57
	s_nop 0
	global_load_lds_dwordx4 v2, s[58:59]
	s_add_i32 m0, s57, 0x2000
	s_nop 0
	global_load_lds_dwordx4 v132, s[58:59]
	s_mov_b32 m0, s7
	s_nop 0
	global_load_lds_dwordx4 v136, s[46:47]
	s_mov_b32 m0, s11
	s_nop 0
	global_load_lds_dwordx4 v134, s[46:47]
	s_waitcnt vmcnt(8)
	s_waitcnt lgkmcnt(0)
	s_barrier
	v_mfma_f32_16x16x32_bf16 v[64:67], v[142:145], v[178:181], v[64:67]
	v_mfma_f32_16x16x32_bf16 v[64:67], v[150:153], v[182:185], v[64:67]
	v_mfma_f32_16x16x32_bf16 v[60:63], v[158:161], v[182:185], v[60:63]
	v_mfma_f32_16x16x32_bf16 v[60:63], v[154:157], v[178:181], v[60:63]
	v_mfma_f32_16x16x32_bf16 v[48:51], v[154:157], v[186:189], v[48:51]
	v_mfma_f32_16x16x32_bf16 v[48:51], v[158:161], v[190:193], v[48:51]
	v_mfma_f32_16x16x32_bf16 v[56:59], v[150:153], v[190:193], v[56:59]
	v_mfma_f32_16x16x32_bf16 v[56:59], v[142:145], v[186:189], v[56:59]
	v_mfma_f32_16x16x32_bf16 v[40:43], v[142:145], v[194:197], v[40:43]
	v_mfma_f32_16x16x32_bf16 v[40:43], v[150:153], v[198:201], v[40:43]
	v_mfma_f32_16x16x32_bf16 v[32:35], v[158:161], v[198:201], v[32:35]
	v_mfma_f32_16x16x32_bf16 v[32:35], v[154:157], v[194:197], v[32:35]
	v_mfma_f32_16x16x32_bf16 v[16:19], v[154:157], v[202:205], v[16:19]
	v_mfma_f32_16x16x32_bf16 v[16:19], v[158:161], v[210:213], v[16:19]
	v_mfma_f32_16x16x32_bf16 v[24:27], v[150:153], v[210:213], v[24:27]
	v_mfma_f32_16x16x32_bf16 v[24:27], v[142:145], v[202:205], v[24:27]
	v_mfma_f32_16x16x32_bf16 v[52:55], v[162:165], v[178:181], v[52:55]
	v_mfma_f32_16x16x32_bf16 v[52:55], v[166:169], v[182:185], v[52:55]
	v_mfma_f32_16x16x32_bf16 v[44:47], v[174:177], v[182:185], v[44:47]
	v_mfma_f32_16x16x32_bf16 v[44:47], v[170:173], v[178:181], v[44:47]
	v_mfma_f32_16x16x32_bf16 v[28:31], v[170:173], v[186:189], v[28:31]
	v_mfma_f32_16x16x32_bf16 v[28:31], v[174:177], v[190:193], v[28:31]
	v_mfma_f32_16x16x32_bf16 v[36:39], v[166:169], v[190:193], v[36:39]
	v_mfma_f32_16x16x32_bf16 v[36:39], v[162:165], v[186:189], v[36:39]
	v_mfma_f32_16x16x32_bf16 v[20:23], v[162:165], v[194:197], v[20:23]
	v_mfma_f32_16x16x32_bf16 v[20:23], v[166:169], v[198:201], v[20:23]
	v_mfma_f32_16x16x32_bf16 v[12:15], v[174:177], v[198:201], v[12:15]
	v_mfma_f32_16x16x32_bf16 v[12:15], v[170:173], v[194:197], v[12:15]
	v_mfma_f32_16x16x32_bf16 v[4:7], v[170:173], v[202:205], v[4:7]
	v_mfma_f32_16x16x32_bf16 v[4:7], v[174:177], v[210:213], v[4:7]
	v_mfma_f32_16x16x32_bf16 v[8:11], v[166:169], v[210:213], v[8:11]
	v_mfma_f32_16x16x32_bf16 v[8:11], v[162:165], v[202:205], v[8:11]
	s_barrier
; #define PG8_STAGE(bufoff, gbase, voff) do { _Pragma("unroll") for (int _i = 0; _i < 2; ++_i) \
;         __builtin_amdgcn_global_load_lds((const unsigned*)((const char*)(gbase) + (voff)[_i]), (PG8_LAS unsigned*)(lds + (bufoff) + ldsw + _i * 8192), 16, 0, 0); } while (0)
; #define PG8_LDA(dst, b, h) do { _Pragma("unroll") for (int m = 0; m < 4; ++m) _Pragma("unroll") for (int k = 0; k < 2; ++k) dst[m][k] = *(const PG8_LAS bf16x8*)(lds + PG8_SA(b, h) + aoff + m * 2048 + k * 1024); } while (0)
; #define PG8_LDB(dst, b, h) do { _Pragma("unroll") for (int n = 0; n < 2; ++n) _Pragma("unroll") for (int k = 0; k < 2; ++k) dst[n][k] = *(const PG8_LAS bf16x8*)(lds + PG8_SB(b, h) + boff + n * 2048 + k * 1024); } while (0)
; #define PG8_MMA(ai, bj, At, Bt) do { __builtin_amdgcn_s_setprio(1); _Pragma("unroll") for (int m = 0; m < 4; ++m) _Pragma("unroll") for (int n = 0; n < 2; ++n) _Pragma("unroll") for (int k = 0; k < 2; ++k) \
;         acc[ai][bj][m][n] = __builtin_amdgcn_mfma_f32_16x16x32_bf16(Bt[n][k], At[m][k], acc[ai][bj][m][n], 0, 0, 0); __builtin_amdgcn_s_setprio(0); } while (0)
; #define PG8_WAIT_V(n) asm volatile("s_waitcnt vmcnt(" #n ")" ::: "memory")
; #define PG8_WAIT_L(n) asm volatile("s_waitcnt lgkmcnt(" #n ")" ::: "memory")
; #define PG8_BAR __builtin_amdgcn_s_barrier()
; #define PG8_SCHED __builtin_amdgcn_sched_barrier(0)
; template <class Epi, class Sched, bool ALIGN_EPI = true>
; __device__ __forceinline__ void gemm_phase(PG8_LAS unsigned char* lds, const Gemm g, const Sched& S, const Epi& E, const int tid) {
;     ...
;             PG8_LDB(B0, 1, 0); PG8_LDB(B1, 1, 1); PG8_SCHED; PG8_LDA(At, 1, 0); PG8_STAGE(PG8_SA(0, 1), a2 + hstepA, voffA);
;             PG8_WAIT_V(8); PG8_WAIT_L(0); PG8_BAR; PG8_MMA(0, 0, At, B0); PG8_MMA(0, 1, At, B1); PG8_BAR; PG8_SCHED;
;             PG8_LDA(At, 1, 1); PG8_STAGE(PG8_SB(1, 0), b3, voffB); PG8_STAGE(PG8_SB(1, 1), b3 + hstepB, voffB); PG8_STAGE(PG8_SA(1, 0), a3, voffA);
;             PG8_WAIT_V(8); PG8_WAIT_L(0); PG8_BAR; PG8_MMA(1, 0, At, B0); PG8_MMA(1, 1, At, B1); PG8_BAR; PG8_SCHED;
	s_add_i32 s57, 0, 0x18000
	s_add_i32 s58, 0, 0x1c000
	v_add_u32_e32 v158, s57, v147
	v_add_u32_e32 v174, s58, v147
	ds_read_b128 v[142:145], v158
	ds_read_b128 v[150:153], v158 offset:1024
	ds_read_b128 v[154:157], v158 offset:2048
	ds_read_b128 v[158:161], v158 offset:3072
	ds_read_b128 v[162:165], v174
	ds_read_b128 v[166:169], v174 offset:1024
	ds_read_b128 v[170:173], v174 offset:2048
	ds_read_b128 v[174:177], v174 offset:3072
	s_add_u32 s46, s46, 0x80000
	s_addc_u32 s47, s47, 0
	s_mov_b32 m0, s30
	ds_read_b128 v[178:181], v149 offset:32768
	ds_read_b128 v[182:185], v149 offset:33792
	ds_read_b128 v[186:189], v149 offset:34816
	ds_read_b128 v[190:193], v149 offset:35840
	ds_read_b128 v[194:197], v149 offset:36864
	ds_read_b128 v[198:201], v149 offset:37888
	ds_read_b128 v[202:205], v149 offset:38912
	ds_read_b128 v[210:213], v149 offset:39936
	global_load_lds_dwordx4 v136, s[46:47]
	s_mov_b32 m0, s48
	s_nop 0
	global_load_lds_dwordx4 v134, s[46:47]
	s_waitcnt vmcnt(8)
	s_waitcnt lgkmcnt(0)
	s_barrier
	v_mfma_f32_16x16x32_bf16 v[128:131], v[142:145], v[178:181], v[128:131]
	v_mfma_f32_16x16x32_bf16 v[128:131], v[150:153], v[182:185], v[128:131]
	v_mfma_f32_16x16x32_bf16 v[124:127], v[158:161], v[182:185], v[124:127]
	v_mfma_f32_16x16x32_bf16 v[124:127], v[154:157], v[178:181], v[124:127]
	v_mfma_f32_16x16x32_bf16 v[112:115], v[154:157], v[186:189], v[112:115]
	v_mfma_f32_16x16x32_bf16 v[112:115], v[158:161], v[190:193], v[112:115]
	v_mfma_f32_16x16x32_bf16 v[120:123], v[150:153], v[190:193], v[120:123]
	v_mfma_f32_16x16x32_bf16 v[120:123], v[142:145], v[186:189], v[120:123]
	v_mfma_f32_16x16x32_bf16 v[104:107], v[142:145], v[194:197], v[104:107]
	v_mfma_f32_16x16x32_bf16 v[104:107], v[150:153], v[198:201], v[104:107]
	v_mfma_f32_16x16x32_bf16 v[96:99], v[158:161], v[198:201], v[96:99]
	v_mfma_f32_16x16x32_bf16 v[96:99], v[154:157], v[194:197], v[96:99]
	v_mfma_f32_16x16x32_bf16 v[80:83], v[154:157], v[202:205], v[80:83]
	v_mfma_f32_16x16x32_bf16 v[80:83], v[158:161], v[210:213], v[80:83]
	v_mfma_f32_16x16x32_bf16 v[88:91], v[150:153], v[210:213], v[88:91]
	v_mfma_f32_16x16x32_bf16 v[88:91], v[142:145], v[202:205], v[88:91]
	v_mfma_f32_16x16x32_bf16 v[116:119], v[162:165], v[178:181], v[116:119]
	v_mfma_f32_16x16x32_bf16 v[116:119], v[166:169], v[182:185], v[116:119]
	v_mfma_f32_16x16x32_bf16 v[108:111], v[174:177], v[182:185], v[108:111]
	v_mfma_f32_16x16x32_bf16 v[108:111], v[170:173], v[178:181], v[108:111]
	v_mfma_f32_16x16x32_bf16 v[92:95], v[170:173], v[186:189], v[92:95]
	v_mfma_f32_16x16x32_bf16 v[92:95], v[174:177], v[190:193], v[92:95]
	v_mfma_f32_16x16x32_bf16 v[100:103], v[166:169], v[190:193], v[100:103]
	v_mfma_f32_16x16x32_bf16 v[100:103], v[162:165], v[186:189], v[100:103]
	v_mfma_f32_16x16x32_bf16 v[84:87], v[162:165], v[194:197], v[84:87]
	v_mfma_f32_16x16x32_bf16 v[84:87], v[166:169], v[198:201], v[84:87]
	v_mfma_f32_16x16x32_bf16 v[76:79], v[174:177], v[198:201], v[76:79]
	v_mfma_f32_16x16x32_bf16 v[76:79], v[170:173], v[194:197], v[76:79]
	v_mfma_f32_16x16x32_bf16 v[68:71], v[170:173], v[202:205], v[68:71]
	v_mfma_f32_16x16x32_bf16 v[68:71], v[174:177], v[210:213], v[68:71]
	v_mfma_f32_16x16x32_bf16 v[72:75], v[166:169], v[210:213], v[72:75]
	v_mfma_f32_16x16x32_bf16 v[72:75], v[162:165], v[202:205], v[72:75]
	s_barrier
	s_add_u32 s96, s46, 0xfff80080
	s_addc_u32 s97, s47, -1
	s_add_i32 s46, s57, s21
	s_mov_b32 m0, s46
	ds_read_b128 v[178:181], v149 offset:49152
	ds_read_b128 v[182:185], v149 offset:50176
	ds_read_b128 v[186:189], v149 offset:51200
	ds_read_b128 v[190:193], v149 offset:52224
	ds_read_b128 v[194:197], v149 offset:53248
	ds_read_b128 v[198:201], v149 offset:54272
	ds_read_b128 v[202:205], v149 offset:55296
	ds_read_b128 v[210:213], v149 offset:56320
	s_add_u32 s98, s44, 0x80
	s_addc_u32 s99, s45, 0
	global_load_lds_dwordx4 v2, s[98:99]
	s_add_i32 m0, s46, 0x2000
	s_add_u32 s44, s44, 0x80080
	s_addc_u32 s45, s45, 0
	s_add_i32 s46, s58, s21
	global_load_lds_dwordx4 v132, s[98:99]
	s_mov_b32 m0, s46
	s_nop 0
	global_load_lds_dwordx4 v2, s[44:45]
	s_add_i32 m0, s46, 0x2000
	s_nop 0
	global_load_lds_dwordx4 v132, s[44:45]
	s_mov_b32 m0, s49
	s_nop 0
	global_load_lds_dwordx4 v136, s[96:97]
	s_mov_b32 m0, s50
	s_nop 0
	global_load_lds_dwordx4 v134, s[96:97]
	s_waitcnt vmcnt(8)
	s_waitcnt lgkmcnt(0)
	s_barrier
	v_mfma_f32_16x16x32_bf16 v[64:67], v[142:145], v[178:181], v[64:67]
	v_mfma_f32_16x16x32_bf16 v[64:67], v[150:153], v[182:185], v[64:67]
	v_mfma_f32_16x16x32_bf16 v[60:63], v[158:161], v[182:185], v[60:63]
	v_mfma_f32_16x16x32_bf16 v[60:63], v[154:157], v[178:181], v[60:63]
	v_mfma_f32_16x16x32_bf16 v[48:51], v[154:157], v[186:189], v[48:51]
	v_mfma_f32_16x16x32_bf16 v[48:51], v[158:161], v[190:193], v[48:51]
	v_mfma_f32_16x16x32_bf16 v[56:59], v[150:153], v[190:193], v[56:59]
	v_mfma_f32_16x16x32_bf16 v[56:59], v[142:145], v[186:189], v[56:59]
	v_mfma_f32_16x16x32_bf16 v[40:43], v[142:145], v[194:197], v[40:43]
	v_mfma_f32_16x16x32_bf16 v[40:43], v[150:153], v[198:201], v[40:43]
	v_mfma_f32_16x16x32_bf16 v[32:35], v[158:161], v[198:201], v[32:35]
	v_mfma_f32_16x16x32_bf16 v[32:35], v[154:157], v[194:197], v[32:35]
	v_mfma_f32_16x16x32_bf16 v[16:19], v[154:157], v[202:205], v[16:19]
	v_mfma_f32_16x16x32_bf16 v[16:19], v[158:161], v[210:213], v[16:19]
	v_mfma_f32_16x16x32_bf16 v[24:27], v[150:153], v[210:213], v[24:27]
	v_mfma_f32_16x16x32_bf16 v[24:27], v[142:145], v[202:205], v[24:27]
	v_mfma_f32_16x16x32_bf16 v[52:55], v[162:165], v[178:181], v[52:55]
	v_mfma_f32_16x16x32_bf16 v[52:55], v[166:169], v[182:185], v[52:55]
	v_mfma_f32_16x16x32_bf16 v[44:47], v[174:177], v[182:185], v[44:47]
	v_mfma_f32_16x16x32_bf16 v[44:47], v[170:173], v[178:181], v[44:47]
	v_mfma_f32_16x16x32_bf16 v[28:31], v[170:173], v[186:189], v[28:31]
	v_mfma_f32_16x16x32_bf16 v[28:31], v[174:177], v[190:193], v[28:31]
	v_mfma_f32_16x16x32_bf16 v[36:39], v[166:169], v[190:193], v[36:39]
	v_mfma_f32_16x16x32_bf16 v[36:39], v[162:165], v[186:189], v[36:39]
	v_mfma_f32_16x16x32_bf16 v[20:23], v[162:165], v[194:197], v[20:23]
	v_mfma_f32_16x16x32_bf16 v[20:23], v[166:169], v[198:201], v[20:23]
	v_mfma_f32_16x16x32_bf16 v[12:15], v[174:177], v[198:201], v[12:15]
	v_mfma_f32_16x16x32_bf16 v[12:15], v[170:173], v[194:197], v[12:15]
	v_mfma_f32_16x16x32_bf16 v[4:7], v[170:173], v[202:205], v[4:7]
	v_mfma_f32_16x16x32_bf16 v[4:7], v[174:177], v[210:213], v[4:7]
	v_mfma_f32_16x16x32_bf16 v[8:11], v[166:169], v[210:213], v[8:11]
	v_mfma_f32_16x16x32_bf16 v[8:11], v[162:165], v[202:205], v[8:11]
	s_barrier
; __device__ __forceinline__ unsigned cvt_pk_bf16(float lo, float hi) { unsigned r; asm volatile("v_cvt_pk_bf16_f32 %0, %1, %2" : "=v"(r) : "v"(lo), "v"(hi)); return r; }
; #define PG8_BAR __builtin_amdgcn_s_barrier()
;     __device__ __forceinline__ void operator()(const f32x4 (&acc)[2][2][4][2], const Unit& u, int wr, int wc, int fr, int fq) const {
;         const int row0 = u.pm * BM + wr * 64 + fr; const int col0 = u.pn * BM + wc * 32 + 8 * fq;
; #pragma unroll
;         for (int ai = 0; ai < 2; ++ai)
; #pragma unroll
;             for (int m = 0; m < 4; ++m) { bf16_t* rowp = O + (size_t)(row0 + ai * HALF + m * 16) * ldc + col0;
; #pragma unroll
;                 for (int bj = 0; bj < 2; ++bj) { const f32x4 v0 = acc[ai][bj][m][0], v1 = acc[ai][bj][m][1];
;                     u32x4 w; w.x = cvt_pk_bf16(v0[0], v0[1]); w.y = cvt_pk_bf16(v0[2], v0[3]); w.z = cvt_pk_bf16(v1[0], v1[1]); w.w = cvt_pk_bf16(v1[2], v1[3]);
;                     *(u32x4*)(rowp + bj * HALF) = w; } }
; template <class Epi, class Sched, bool ALIGN_EPI = true>
; __device__ __forceinline__ void gemm_phase(PG8_LAS unsigned char* lds, const Gemm g, const Sched& S, const Epi& E, const int tid) {
;     ...
;         }
;         if constexpr (ALIGN_EPI) { if (wr == 0) PG8_BAR; }
;         E(acc, cur, wr, wc, fr, fq); S.done(cur);
;         if (!has_next) break;
	s_add_i32 s56, s56, 2
	s_add_u32 s42, s42, 0x100
	s_addc_u32 s43, s43, 0
	s_add_u32 s54, s54, 0x100
	s_addc_u32 s55, s55, 0
	s_cmp_gt_u32 s56, 29
	s_cbranch_scc0 .LBB0_514
	v_lshl_or_b32 v144, s10, 8, v148
	v_lshl_add_u32 v152, s6, 8, v146
	v_ashrrev_i32_e32 v145, 31, v144
	v_mov_b64_e32 v[142:143], s[0:1]
	s_movk_i32 s3, 0x3200
	v_mad_i64_i32 v[150:151], s[42:43], v152, s3, v[142:143]
	v_lshlrev_b64 v[144:145], 1, v[144:145]
	v_lshl_add_u64 v[150:151], v[150:151], 0, v[144:145]
	v_cvt_pk_bf16_f32 v128, v128, v129
	v_cvt_pk_bf16_f32 v129, v130, v131
	v_cvt_pk_bf16_f32 v130, v124, v125
	v_cvt_pk_bf16_f32 v131, v126, v127
	global_store_dwordx4 v[150:151], v[128:131], off
	v_cvt_pk_bf16_f32 v116, v116, v117
	v_cvt_pk_bf16_f32 v117, v118, v119
	v_cvt_pk_bf16_f32 v118, v108, v109
	v_or_b32_e32 v108, 16, v152
	v_mad_i64_i32 v[108:109], s[42:43], v108, s3, v[142:143]
	v_cvt_pk_bf16_f32 v119, v110, v111
	global_store_dwordx4 v[150:151], v[116:119], off offset:256
	s_and_b64 vcc, exec, s[4:5]
	s_mov_b32 s10, s22
	v_lshl_add_u64 v[116:117], v[108:109], 0, v[144:145]
	v_cvt_pk_bf16_f32 v108, v120, v121
	v_cvt_pk_bf16_f32 v109, v122, v123
	v_cvt_pk_bf16_f32 v110, v112, v113
	v_cvt_pk_bf16_f32 v111, v114, v115
	global_store_dwordx4 v[116:117], v[108:111], off
	v_cvt_pk_bf16_f32 v100, v100, v101
	v_cvt_pk_bf16_f32 v101, v102, v103
	v_cvt_pk_bf16_f32 v102, v92, v93
	v_or_b32_e32 v92, 32, v152
	v_mad_i64_i32 v[92:93], s[42:43], v92, s3, v[142:143]
	v_cvt_pk_bf16_f32 v103, v94, v95
	global_store_dwordx4 v[116:117], v[100:103], off offset:256
	s_mov_b32 s6, s12
	s_mov_b64 s[44:45], s[40:41]
	v_lshl_add_u64 v[100:101], v[92:93], 0, v[144:145]
	v_cvt_pk_bf16_f32 v92, v104, v105
	v_cvt_pk_bf16_f32 v93, v106, v107
	v_cvt_pk_bf16_f32 v94, v96, v97
	v_cvt_pk_bf16_f32 v95, v98, v99
	global_store_dwordx4 v[100:101], v[92:95], off
	v_cvt_pk_bf16_f32 v84, v84, v85
	v_cvt_pk_bf16_f32 v85, v86, v87
	v_cvt_pk_bf16_f32 v86, v76, v77
	v_or_b32_e32 v76, 48, v152
	v_mad_i64_i32 v[76:77], s[42:43], v76, s3, v[142:143]
	v_cvt_pk_bf16_f32 v87, v78, v79
	global_store_dwordx4 v[100:101], v[84:87], off offset:256
	s_nop 1
	v_lshl_add_u64 v[84:85], v[76:77], 0, v[144:145]
	v_cvt_pk_bf16_f32 v76, v88, v89
	v_cvt_pk_bf16_f32 v77, v90, v91
	v_cvt_pk_bf16_f32 v78, v80, v81
	v_cvt_pk_bf16_f32 v79, v82, v83
	global_store_dwordx4 v[84:85], v[76:79], off
	v_cvt_pk_bf16_f32 v72, v72, v73
	v_cvt_pk_bf16_f32 v73, v74, v75
	v_cvt_pk_bf16_f32 v74, v68, v69
	v_add_u32_e32 v68, 0x80, v152
	v_mad_i64_i32 v[68:69], s[42:43], v68, s3, v[142:143]
	v_lshl_add_u64 v[68:69], v[68:69], 0, v[144:145]
	v_cvt_pk_bf16_f32 v75, v70, v71
	global_store_dwordx4 v[84:85], v[72:75], off offset:256
	v_cvt_pk_bf16_f32 v64, v64, v65
	v_cvt_pk_bf16_f32 v65, v66, v67
	v_cvt_pk_bf16_f32 v66, v60, v61
	v_cvt_pk_bf16_f32 v67, v62, v63
	global_store_dwordx4 v[68:69], v[64:67], off
	v_cvt_pk_bf16_f32 v52, v52, v53
	v_cvt_pk_bf16_f32 v53, v54, v55
	v_cvt_pk_bf16_f32 v54, v44, v45
	v_add_u32_e32 v44, 0x90, v152
	v_mad_i64_i32 v[44:45], s[42:43], v44, s3, v[142:143]
	v_cvt_pk_bf16_f32 v55, v46, v47
	global_store_dwordx4 v[68:69], v[52:55], off offset:256
	s_nop 1
	v_lshl_add_u64 v[52:53], v[44:45], 0, v[144:145]
	v_cvt_pk_bf16_f32 v44, v56, v57
	v_cvt_pk_bf16_f32 v45, v58, v59
	v_cvt_pk_bf16_f32 v46, v48, v49
	v_cvt_pk_bf16_f32 v47, v50, v51
	global_store_dwordx4 v[52:53], v[44:47], off
	v_cvt_pk_bf16_f32 v36, v36, v37
	v_cvt_pk_bf16_f32 v37, v38, v39
	v_cvt_pk_bf16_f32 v38, v28, v29
	v_add_u32_e32 v28, 0xa0, v152
	v_mad_i64_i32 v[28:29], s[42:43], v28, s3, v[142:143]
	v_cvt_pk_bf16_f32 v39, v30, v31
	global_store_dwordx4 v[52:53], v[36:39], off offset:256
	s_nop 1
	v_lshl_add_u64 v[36:37], v[28:29], 0, v[144:145]
	v_cvt_pk_bf16_f32 v28, v40, v41
	v_cvt_pk_bf16_f32 v29, v42, v43
	v_cvt_pk_bf16_f32 v30, v32, v33
	v_cvt_pk_bf16_f32 v31, v34, v35
	global_store_dwordx4 v[36:37], v[28:31], off
	v_cvt_pk_bf16_f32 v20, v20, v21
	v_cvt_pk_bf16_f32 v21, v22, v23
	v_cvt_pk_bf16_f32 v22, v12, v13
	v_add_u32_e32 v12, 0xb0, v152
	v_mad_i64_i32 v[12:13], s[42:43], v12, s3, v[142:143]
	v_cvt_pk_bf16_f32 v23, v14, v15
	global_store_dwordx4 v[36:37], v[20:23], off offset:256
	s_mov_b64 s[42:43], s[38:39]
	s_nop 0
	v_lshl_add_u64 v[20:21], v[12:13], 0, v[144:145]
	v_cvt_pk_bf16_f32 v12, v24, v25
	v_cvt_pk_bf16_f32 v13, v26, v27
	v_cvt_pk_bf16_f32 v14, v16, v17
	v_cvt_pk_bf16_f32 v15, v18, v19
	global_store_dwordx4 v[20:21], v[12:15], off
	v_cvt_pk_bf16_f32 v8, v8, v9
	v_cvt_pk_bf16_f32 v9, v10, v11
	v_cvt_pk_bf16_f32 v10, v4, v5
	v_cvt_pk_bf16_f32 v11, v6, v7
	global_store_dwordx4 v[20:21], v[8:11], off offset:256
	s_cbranch_vccz .LBB0_507
	s_waitcnt vmcnt(0)
	s_cmpk_gt_u32 s8, 0xff
	s_cbranch_scc1 .LBB0_518
	s_barrier

; #define PG8_STAGE(bufoff, gbase, voff) do { _Pragma("unroll") for (int _i = 0; _i < 2; ++_i) \
;         __builtin_amdgcn_global_load_lds((const unsigned*)((const char*)(gbase) + (voff)[_i]), (PG8_LAS unsigned*)(lds + (bufoff) + ldsw + _i * 8192), 16, 0, 0); } while (0)
; #define PG8_LDA(dst, b, h) do { _Pragma("unroll") for (int m = 0; m < 4; ++m) _Pragma("unroll") for (int k = 0; k < 2; ++k) dst[m][k] = *(const PG8_LAS bf16x8*)(lds + PG8_SA(b, h) + aoff + m * 2048 + k * 1024); } while (0)
; #define PG8_LDB(dst, b, h) do { _Pragma("unroll") for (int n = 0; n < 2; ++n) _Pragma("unroll") for (int k = 0; k < 2; ++k) dst[n][k] = *(const PG8_LAS bf16x8*)(lds + PG8_SB(b, h) + boff + n * 2048 + k * 1024); } while (0)
; #define PG8_MMA(ai, bj, At, Bt) do { __builtin_amdgcn_s_setprio(1); _Pragma("unroll") for (int m = 0; m < 4; ++m) _Pragma("unroll") for (int n = 0; n < 2; ++n) _Pragma("unroll") for (int k = 0; k < 2; ++k) \
;         acc[ai][bj][m][n] = __builtin_amdgcn_mfma_f32_16x16x32_bf16(Bt[n][k], At[m][k], acc[ai][bj][m][n], 0, 0, 0); __builtin_amdgcn_s_setprio(0); } while (0)
; #define PG8_WAIT_V(n) asm volatile("s_waitcnt vmcnt(" #n ")" ::: "memory")
; #define PG8_WAIT_L(n) asm volatile("s_waitcnt lgkmcnt(" #n ")" ::: "memory")
; #define PG8_BAR __builtin_amdgcn_s_barrier()
; template <class Epi, class Sched, bool ALIGN_EPI = true>
; __device__ __forceinline__ void gemm_phase(PG8_LAS unsigned char* lds, const Gemm g, const Sched& S, const Epi& E, const int tid) {
;     ...
;             const bool last = (t == nt - 2);
;             const char* a1 = cA + (size_t)(t + 1) * kstep;
;             const char* a2 = last ? nA : cA + (size_t)(t + 2) * kstep; const char* b2 = last ? nB : cB + (size_t)(t + 2) * kstep;
;             const char* a3 = a2 + kstep; const char* b3 = b2 + kstep;
;             if (last && has_next) S.a_ready(nxt);
;             PG8_LDB(B0, 0, 0); PG8_LDB(B1, 0, 1); PG8_SCHED; PG8_LDA(At, 0, 0); PG8_STAGE(PG8_SA(1, 1), a1 + hstepA, voffA);
;             PG8_WAIT_V(8); PG8_WAIT_L(0); PG8_BAR; PG8_MMA(0, 0, At, B0); PG8_MMA(0, 1, At, B1); PG8_BAR; PG8_SCHED;
;             PG8_LDA(At, 0, 1); PG8_STAGE(PG8_SB(0, 0), b2, voffB); PG8_STAGE(PG8_SB(0, 1), b2 + hstepB, voffB); PG8_STAGE(PG8_SA(0, 0), a2, voffA);
;             PG8_WAIT_V(8); PG8_WAIT_L(0); PG8_BAR; PG8_MMA(1, 0, At, B0); PG8_MMA(1, 1, At, B1); PG8_BAR; PG8_SCHED;
.LBB0_1087:
	s_add_i32 s45, s22, 2
	s_add_u32 s15, s12, 0xfff80080
	s_addc_u32 s16, s13, -1
	s_add_i32 s17, 0, 0x10000
	s_cmp_eq_u32 s1, s22
	s_cselect_b32 s55, s51, s16
	s_cselect_b32 s54, s50, s15
	s_cselect_b32 s23, s53, s21
	s_cselect_b32 s22, s52, s20
	s_add_i32 s15, 0, 0x14000
	v_add_u32_e32 v72, s17, v251
	v_add_u32_e32 v128, s15, v251
	ds_read_b128 v[56:59], v72
	ds_read_b128 v[64:67], v72 offset:1024
	ds_read_b128 v[68:71], v72 offset:2048
	ds_read_b128 v[72:75], v72 offset:3072
	ds_read_b128 v[92:95], v128
	ds_read_b128 v[104:107], v128 offset:1024
	ds_read_b128 v[116:119], v128 offset:2048
	ds_read_b128 v[128:131], v128 offset:3072
	s_add_i32 m0, s11, 0xc000
	ds_read_b128 v[140:143], v252
	ds_read_b128 v[152:155], v252 offset:1024
	ds_read_b128 v[156:159], v252 offset:2048
	ds_read_b128 v[160:163], v252 offset:3072
	ds_read_b128 v[172:175], v252 offset:4096
	ds_read_b128 v[184:187], v252 offset:5120
	ds_read_b128 v[188:191], v252 offset:6144
	ds_read_b128 v[192:195], v252 offset:7168
	global_load_lds_dwordx4 v216, s[12:13]
	s_add_i32 m0, s11, 0xe000
	s_nop 0
	global_load_lds_dwordx4 v218, s[12:13]
	s_waitcnt vmcnt(8)
	s_waitcnt lgkmcnt(0)
	s_barrier
	v_mfma_f32_16x16x32_bf16 v[180:183], v[56:59], v[140:143], v[180:183]
	v_mfma_f32_16x16x32_bf16 v[180:183], v[64:67], v[152:155], v[180:183]
	v_mfma_f32_16x16x32_bf16 v[176:179], v[72:75], v[152:155], v[176:179]
	v_mfma_f32_16x16x32_bf16 v[176:179], v[68:71], v[140:143], v[176:179]
	v_mfma_f32_16x16x32_bf16 v[144:147], v[68:71], v[156:159], v[144:147]
	v_mfma_f32_16x16x32_bf16 v[144:147], v[72:75], v[160:163], v[144:147]
	v_mfma_f32_16x16x32_bf16 v[148:151], v[64:67], v[160:163], v[148:151]
	v_mfma_f32_16x16x32_bf16 v[148:151], v[56:59], v[156:159], v[148:151]
	v_mfma_f32_16x16x32_bf16 v[124:127], v[56:59], v[172:175], v[124:127]
	v_mfma_f32_16x16x32_bf16 v[124:127], v[64:67], v[184:187], v[124:127]
	v_mfma_f32_16x16x32_bf16 v[120:123], v[72:75], v[184:187], v[120:123]
	v_mfma_f32_16x16x32_bf16 v[120:123], v[68:71], v[172:175], v[120:123]
	v_mfma_f32_16x16x32_bf16 v[96:99], v[68:71], v[188:191], v[96:99]
	v_mfma_f32_16x16x32_bf16 v[96:99], v[72:75], v[192:195], v[96:99]
	v_mfma_f32_16x16x32_bf16 v[100:103], v[64:67], v[192:195], v[100:103]
	v_mfma_f32_16x16x32_bf16 v[100:103], v[56:59], v[188:191], v[100:103]
	v_mfma_f32_16x16x32_bf16 v[168:171], v[92:95], v[140:143], v[168:171]
	v_mfma_f32_16x16x32_bf16 v[168:171], v[104:107], v[152:155], v[168:171]
	v_mfma_f32_16x16x32_bf16 v[136:139], v[104:107], v[160:163], v[136:139]
	v_mfma_f32_16x16x32_bf16 v[136:139], v[92:95], v[156:159], v[136:139]
	v_mfma_f32_16x16x32_bf16 v[132:135], v[116:119], v[156:159], v[132:135]
	v_mfma_f32_16x16x32_bf16 v[132:135], v[128:131], v[160:163], v[132:135]
	v_mfma_f32_16x16x32_bf16 v[108:111], v[128:131], v[184:187], v[108:111]
	v_mfma_f32_16x16x32_bf16 v[108:111], v[116:119], v[172:175], v[108:111]
	v_mfma_f32_16x16x32_bf16 v[112:115], v[92:95], v[172:175], v[112:115]
	v_mfma_f32_16x16x32_bf16 v[112:115], v[104:107], v[184:187], v[112:115]
	v_mfma_f32_16x16x32_bf16 v[88:91], v[104:107], v[192:195], v[88:91]
	v_mfma_f32_16x16x32_bf16 v[88:91], v[92:95], v[188:191], v[88:91]
	v_mfma_f32_16x16x32_bf16 v[84:87], v[116:119], v[188:191], v[84:87]
	v_mfma_f32_16x16x32_bf16 v[84:87], v[128:131], v[192:195], v[84:87]
	v_mfma_f32_16x16x32_bf16 v[140:143], v[116:119], v[140:143], v[164:167]
	v_mfma_f32_16x16x32_bf16 v[140:143], v[128:131], v[152:155], v[140:143]
	s_barrier
	s_add_i32 s16, s17, s60
	s_mov_b32 m0, s16
	ds_read_b128 v[152:155], v252 offset:16384
	ds_read_b128 v[156:159], v252 offset:17408
	ds_read_b128 v[160:163], v252 offset:18432
	ds_read_b128 v[164:167], v252 offset:19456
	ds_read_b128 v[172:175], v252 offset:20480
	ds_read_b128 v[184:187], v252 offset:21504
	ds_read_b128 v[188:191], v252 offset:22528
	ds_read_b128 v[192:195], v252 offset:23552
	global_load_lds_dwordx4 v2, s[22:23]
	s_add_i32 m0, s16, 0x2000
	s_add_u32 s72, s22, 0x80000
	s_addc_u32 s73, s23, 0
	s_add_i32 s15, s15, s60
	global_load_lds_dwordx4 v214, s[22:23]
	s_mov_b32 m0, s15
	s_nop 0
	global_load_lds_dwordx4 v2, s[72:73]
	s_add_i32 m0, s15, 0x2000
	s_nop 0
	global_load_lds_dwordx4 v214, s[72:73]
	s_mov_b32 m0, s11
	s_nop 0
	global_load_lds_dwordx4 v210, s[54:55]
	s_mov_b32 m0, s61
	s_nop 0
	global_load_lds_dwordx4 v212, s[54:55]
	s_waitcnt vmcnt(8)
	s_waitcnt lgkmcnt(0)
	s_barrier
	v_mfma_f32_16x16x32_bf16 v[80:83], v[56:59], v[152:155], v[80:83]
	v_mfma_f32_16x16x32_bf16 v[80:83], v[64:67], v[156:159], v[80:83]
	v_mfma_f32_16x16x32_bf16 v[76:79], v[72:75], v[156:159], v[76:79]
	v_mfma_f32_16x16x32_bf16 v[76:79], v[68:71], v[152:155], v[76:79]
	v_mfma_f32_16x16x32_bf16 v[44:47], v[68:71], v[160:163], v[44:47]
	v_mfma_f32_16x16x32_bf16 v[44:47], v[72:75], v[164:167], v[44:47]
	v_mfma_f32_16x16x32_bf16 v[48:51], v[64:67], v[164:167], v[48:51]
	v_mfma_f32_16x16x32_bf16 v[48:51], v[56:59], v[160:163], v[48:51]
	v_mfma_f32_16x16x32_bf16 v[32:35], v[56:59], v[172:175], v[32:35]
	v_mfma_f32_16x16x32_bf16 v[32:35], v[64:67], v[184:187], v[32:35]
	v_mfma_f32_16x16x32_bf16 v[28:31], v[72:75], v[184:187], v[28:31]
	v_mfma_f32_16x16x32_bf16 v[28:31], v[68:71], v[172:175], v[28:31]
	v_mfma_f32_16x16x32_bf16 v[12:15], v[68:71], v[188:191], v[12:15]
	v_mfma_f32_16x16x32_bf16 v[12:15], v[72:75], v[192:195], v[12:15]
	v_mfma_f32_16x16x32_bf16 v[16:19], v[64:67], v[192:195], v[16:19]
	v_mfma_f32_16x16x32_bf16 v[16:19], v[56:59], v[188:191], v[16:19]
	v_mfma_f32_16x16x32_bf16 v[52:55], v[116:119], v[152:155], v[52:55]
	v_mfma_f32_16x16x32_bf16 v[52:55], v[128:131], v[156:159], v[52:55]
	v_mfma_f32_16x16x32_bf16 v[36:39], v[128:131], v[164:167], v[36:39]
	v_mfma_f32_16x16x32_bf16 v[36:39], v[116:119], v[160:163], v[36:39]
	v_mfma_f32_16x16x32_bf16 v[40:43], v[92:95], v[160:163], v[40:43]
	v_mfma_f32_16x16x32_bf16 v[40:43], v[104:107], v[164:167], v[40:43]
	v_mfma_f32_16x16x32_bf16 v[24:27], v[104:107], v[184:187], v[24:27]
	v_mfma_f32_16x16x32_bf16 v[24:27], v[92:95], v[172:175], v[24:27]
	v_mfma_f32_16x16x32_bf16 v[20:23], v[116:119], v[172:175], v[20:23]
	v_mfma_f32_16x16x32_bf16 v[20:23], v[128:131], v[184:187], v[20:23]
	v_mfma_f32_16x16x32_bf16 v[4:7], v[128:131], v[192:195], v[4:7]
	v_mfma_f32_16x16x32_bf16 v[4:7], v[116:119], v[188:191], v[4:7]
	v_mfma_f32_16x16x32_bf16 v[8:11], v[92:95], v[188:191], v[8:11]
	v_mfma_f32_16x16x32_bf16 v[8:11], v[104:107], v[192:195], v[8:11]
	v_mfma_f32_16x16x32_bf16 v[56:59], v[92:95], v[152:155], v[60:63]
	v_mfma_f32_16x16x32_bf16 v[56:59], v[104:107], v[156:159], v[56:59]
	s_barrier
; #define PG8_STAGE(bufoff, gbase, voff) do { _Pragma("unroll") for (int _i = 0; _i < 2; ++_i) \
;         __builtin_amdgcn_global_load_lds((const unsigned*)((const char*)(gbase) + (voff)[_i]), (PG8_LAS unsigned*)(lds + (bufoff) + ldsw + _i * 8192), 16, 0, 0); } while (0)
; #define PG8_LDA(dst, b, h) do { _Pragma("unroll") for (int m = 0; m < 4; ++m) _Pragma("unroll") for (int k = 0; k < 2; ++k) dst[m][k] = *(const PG8_LAS bf16x8*)(lds + PG8_SA(b, h) + aoff + m * 2048 + k * 1024); } while (0)
; #define PG8_LDB(dst, b, h) do { _Pragma("unroll") for (int n = 0; n < 2; ++n) _Pragma("unroll") for (int k = 0; k < 2; ++k) dst[n][k] = *(const PG8_LAS bf16x8*)(lds + PG8_SB(b, h) + boff + n * 2048 + k * 1024); } while (0)
; #define PG8_MMA(ai, bj, At, Bt) do { __builtin_amdgcn_s_setprio(1); _Pragma("unroll") for (int m = 0; m < 4; ++m) _Pragma("unroll") for (int n = 0; n < 2; ++n) _Pragma("unroll") for (int k = 0; k < 2; ++k) \
;         acc[ai][bj][m][n] = __builtin_amdgcn_mfma_f32_16x16x32_bf16(Bt[n][k], At[m][k], acc[ai][bj][m][n], 0, 0, 0); __builtin_amdgcn_s_setprio(0); } while (0)
; #define PG8_WAIT_V(n) asm volatile("s_waitcnt vmcnt(" #n ")" ::: "memory")
; #define PG8_WAIT_L(n) asm volatile("s_waitcnt lgkmcnt(" #n ")" ::: "memory")
; #define PG8_BAR __builtin_amdgcn_s_barrier()
; #define PG8_SCHED __builtin_amdgcn_sched_barrier(0)
; template <class Epi, class Sched, bool ALIGN_EPI = true>
; __device__ __forceinline__ void gemm_phase(PG8_LAS unsigned char* lds, const Gemm g, const Sched& S, const Epi& E, const int tid) {
;     ...
;             PG8_LDB(B0, 1, 0); PG8_LDB(B1, 1, 1); PG8_SCHED; PG8_LDA(At, 1, 0); PG8_STAGE(PG8_SA(0, 1), a2 + hstepA, voffA);
;             PG8_WAIT_V(8); PG8_WAIT_L(0); PG8_BAR; PG8_MMA(0, 0, At, B0); PG8_MMA(0, 1, At, B1); PG8_BAR; PG8_SCHED;
;             PG8_LDA(At, 1, 1); PG8_STAGE(PG8_SB(1, 0), b3, voffB); PG8_STAGE(PG8_SB(1, 1), b3 + hstepB, voffB); PG8_STAGE(PG8_SA(1, 0), a3, voffA);
;             PG8_WAIT_V(8); PG8_WAIT_L(0); PG8_BAR; PG8_MMA(1, 0, At, B0); PG8_MMA(1, 1, At, B1); PG8_BAR; PG8_SCHED;
;         }
;         if constexpr (ALIGN_EPI) { if (wr == 0) PG8_BAR; }
	s_add_i32 s15, 0, 0x18000
	s_add_i32 s16, 0, 0x1c000
	v_add_u32_e32 v72, s15, v251
	v_add_u32_e32 v128, s16, v251
	ds_read_b128 v[60:63], v72
	ds_read_b128 v[64:67], v72 offset:1024
	ds_read_b128 v[68:71], v72 offset:2048
	ds_read_b128 v[72:75], v72 offset:3072
	ds_read_b128 v[92:95], v128
	ds_read_b128 v[104:107], v128 offset:1024
	ds_read_b128 v[116:119], v128 offset:2048
	ds_read_b128 v[128:131], v128 offset:3072
	s_add_u32 s54, s54, 0x80000
	s_addc_u32 s55, s55, 0
	s_mov_b32 m0, s62
	ds_read_b128 v[152:155], v252 offset:32768
	ds_read_b128 v[156:159], v252 offset:33792
	ds_read_b128 v[160:163], v252 offset:34816
	ds_read_b128 v[172:175], v252 offset:35840
	ds_read_b128 v[184:187], v252 offset:36864
	ds_read_b128 v[188:191], v252 offset:37888
	ds_read_b128 v[192:195], v252 offset:38912
	ds_read_b128 v[196:199], v252 offset:39936
	global_load_lds_dwordx4 v210, s[54:55]
	s_mov_b32 m0, s63
	s_nop 0
	global_load_lds_dwordx4 v212, s[54:55]
	s_waitcnt vmcnt(8)
	s_waitcnt lgkmcnt(0)
	s_barrier
	v_mfma_f32_16x16x32_bf16 v[164:167], v[60:63], v[152:155], v[180:183]
	v_mfma_f32_16x16x32_bf16 v[180:183], v[64:67], v[156:159], v[164:167]
	v_mfma_f32_16x16x32_bf16 v[148:151], v[64:67], v[172:175], v[148:151]
	v_mfma_f32_16x16x32_bf16 v[148:151], v[60:63], v[160:163], v[148:151]
	v_mfma_f32_16x16x32_bf16 v[144:147], v[68:71], v[160:163], v[144:147]
	v_mfma_f32_16x16x32_bf16 v[144:147], v[72:75], v[172:175], v[144:147]
	v_mfma_f32_16x16x32_bf16 v[120:123], v[72:75], v[188:191], v[120:123]
	v_mfma_f32_16x16x32_bf16 v[120:123], v[68:71], v[184:187], v[120:123]
	v_mfma_f32_16x16x32_bf16 v[164:167], v[68:71], v[152:155], v[176:179]
	v_mfma_f32_16x16x32_bf16 v[176:179], v[72:75], v[156:159], v[164:167]
	v_mfma_f32_16x16x32_bf16 v[96:99], v[72:75], v[196:199], v[96:99]
	v_mfma_f32_16x16x32_bf16 v[96:99], v[68:71], v[192:195], v[96:99]
	v_mfma_f32_16x16x32_bf16 v[100:103], v[60:63], v[192:195], v[100:103]
	v_mfma_f32_16x16x32_bf16 v[100:103], v[64:67], v[196:199], v[100:103]
	v_mfma_f32_16x16x32_bf16 v[124:127], v[64:67], v[188:191], v[124:127]
	v_mfma_f32_16x16x32_bf16 v[124:127], v[60:63], v[184:187], v[124:127]
	v_mfma_f32_16x16x32_bf16 v[164:167], v[92:95], v[152:155], v[168:171]
	v_mfma_f32_16x16x32_bf16 v[168:171], v[104:107], v[156:159], v[164:167]
	v_mfma_f32_16x16x32_bf16 v[136:139], v[104:107], v[172:175], v[136:139]
	v_mfma_f32_16x16x32_bf16 v[136:139], v[92:95], v[160:163], v[136:139]
	v_mfma_f32_16x16x32_bf16 v[132:135], v[116:119], v[160:163], v[132:135]
	v_mfma_f32_16x16x32_bf16 v[132:135], v[128:131], v[172:175], v[132:135]
	v_mfma_f32_16x16x32_bf16 v[108:111], v[128:131], v[188:191], v[108:111]
	v_mfma_f32_16x16x32_bf16 v[108:111], v[116:119], v[184:187], v[108:111]
	v_mfma_f32_16x16x32_bf16 v[140:143], v[116:119], v[152:155], v[140:143]
	v_mfma_f32_16x16x32_bf16 v[164:167], v[128:131], v[156:159], v[140:143]
	v_mfma_f32_16x16x32_bf16 v[84:87], v[128:131], v[196:199], v[84:87]
	v_mfma_f32_16x16x32_bf16 v[84:87], v[116:119], v[192:195], v[84:87]
	v_mfma_f32_16x16x32_bf16 v[88:91], v[92:95], v[192:195], v[88:91]
	v_mfma_f32_16x16x32_bf16 v[88:91], v[104:107], v[196:199], v[88:91]
	v_mfma_f32_16x16x32_bf16 v[112:115], v[104:107], v[188:191], v[112:115]
	v_mfma_f32_16x16x32_bf16 v[112:115], v[92:95], v[184:187], v[112:115]
	s_barrier
	s_add_i32 s15, s15, s60
	s_mov_b32 m0, s15
	ds_read_b128 v[140:143], v252 offset:49152
	ds_read_b128 v[152:155], v252 offset:50176
	ds_read_b128 v[156:159], v252 offset:51200
	ds_read_b128 v[160:163], v252 offset:52224
	ds_read_b128 v[172:175], v252 offset:53248
	ds_read_b128 v[184:187], v252 offset:54272
	ds_read_b128 v[188:191], v252 offset:55296
	ds_read_b128 v[192:195], v252 offset:56320
	s_add_u32 s98, s22, 0x80
	s_addc_u32 s99, s23, 0
	global_load_lds_dwordx4 v2, s[98:99]
	s_add_i32 m0, s15, 0x2000
	s_add_u32 s22, s22, 0x80080
	s_addc_u32 s23, s23, 0
	s_add_i32 s15, s16, s60
	global_load_lds_dwordx4 v214, s[98:99]
	s_mov_b32 m0, s15
	s_nop 0
	global_load_lds_dwordx4 v2, s[22:23]
	s_add_i32 m0, s15, 0x2000
	s_nop 0
	global_load_lds_dwordx4 v214, s[22:23]
	s_mov_b32 m0, s68
	s_nop 0
	s_add_u32 s98, s54, 0xfff80080
	s_addc_u32 s99, s55, -1
	global_load_lds_dwordx4 v210, s[98:99]
	s_mov_b32 m0, s69
	s_nop 0
	global_load_lds_dwordx4 v212, s[98:99]
	s_waitcnt vmcnt(8)
	s_waitcnt lgkmcnt(0)
	s_barrier
	v_mfma_f32_16x16x32_bf16 v[80:83], v[60:63], v[140:143], v[80:83]
	v_mfma_f32_16x16x32_bf16 v[80:83], v[64:67], v[152:155], v[80:83]
	v_mfma_f32_16x16x32_bf16 v[76:79], v[72:75], v[152:155], v[76:79]
	v_mfma_f32_16x16x32_bf16 v[76:79], v[68:71], v[140:143], v[76:79]
	v_mfma_f32_16x16x32_bf16 v[44:47], v[68:71], v[156:159], v[44:47]
	v_mfma_f32_16x16x32_bf16 v[44:47], v[72:75], v[160:163], v[44:47]
	v_mfma_f32_16x16x32_bf16 v[48:51], v[64:67], v[160:163], v[48:51]
	v_mfma_f32_16x16x32_bf16 v[48:51], v[60:63], v[156:159], v[48:51]
	v_mfma_f32_16x16x32_bf16 v[32:35], v[60:63], v[172:175], v[32:35]
	v_mfma_f32_16x16x32_bf16 v[32:35], v[64:67], v[184:187], v[32:35]
	v_mfma_f32_16x16x32_bf16 v[28:31], v[72:75], v[184:187], v[28:31]
	v_mfma_f32_16x16x32_bf16 v[28:31], v[68:71], v[172:175], v[28:31]
	v_mfma_f32_16x16x32_bf16 v[12:15], v[68:71], v[188:191], v[12:15]
	v_mfma_f32_16x16x32_bf16 v[12:15], v[72:75], v[192:195], v[12:15]
	v_mfma_f32_16x16x32_bf16 v[16:19], v[64:67], v[192:195], v[16:19]
	v_mfma_f32_16x16x32_bf16 v[16:19], v[60:63], v[188:191], v[16:19]
	v_mfma_f32_16x16x32_bf16 v[56:59], v[92:95], v[140:143], v[56:59]
	v_mfma_f32_16x16x32_bf16 v[60:63], v[104:107], v[152:155], v[56:59]
	v_mfma_f32_16x16x32_bf16 v[52:55], v[128:131], v[152:155], v[52:55]
	v_mfma_f32_16x16x32_bf16 v[52:55], v[116:119], v[140:143], v[52:55]
	v_mfma_f32_16x16x32_bf16 v[36:39], v[116:119], v[156:159], v[36:39]
	v_mfma_f32_16x16x32_bf16 v[36:39], v[128:131], v[160:163], v[36:39]
	v_mfma_f32_16x16x32_bf16 v[40:43], v[104:107], v[160:163], v[40:43]
	v_mfma_f32_16x16x32_bf16 v[40:43], v[92:95], v[156:159], v[40:43]
	v_mfma_f32_16x16x32_bf16 v[24:27], v[92:95], v[172:175], v[24:27]
	v_mfma_f32_16x16x32_bf16 v[24:27], v[104:107], v[184:187], v[24:27]
	v_mfma_f32_16x16x32_bf16 v[20:23], v[128:131], v[184:187], v[20:23]
	v_mfma_f32_16x16x32_bf16 v[20:23], v[116:119], v[172:175], v[20:23]
	v_mfma_f32_16x16x32_bf16 v[4:7], v[116:119], v[188:191], v[4:7]
	v_mfma_f32_16x16x32_bf16 v[4:7], v[128:131], v[192:195], v[4:7]
	v_mfma_f32_16x16x32_bf16 v[8:11], v[104:107], v[192:195], v[8:11]
	v_mfma_f32_16x16x32_bf16 v[8:11], v[92:95], v[188:191], v[8:11]
	s_barrier
	s_add_u32 s12, s12, 0x100
	s_addc_u32 s13, s13, 0
	s_add_u32 s20, s20, 0x100
	s_addc_u32 s21, s21, 0
	s_cmp_ge_i32 s45, s9
	s_mov_b32 s22, s45
	s_cbranch_scc0 .LBB0_1087
	s_and_b64 vcc, exec, s[42:43]
	s_cbranch_vccz .LBB0_1090
	s_barrier

; #define PG8_STAGE(bufoff, gbase, voff) do { _Pragma("unroll") for (int _i = 0; _i < 2; ++_i) \
;         __builtin_amdgcn_global_load_lds((const unsigned*)((const char*)(gbase) + (voff)[_i]), (PG8_LAS unsigned*)(lds + (bufoff) + ldsw + _i * 8192), 16, 0, 0); } while (0)
; #define PG8_LDA(dst, b, h) do { _Pragma("unroll") for (int m = 0; m < 4; ++m) _Pragma("unroll") for (int k = 0; k < 2; ++k) dst[m][k] = *(const PG8_LAS bf16x8*)(lds + PG8_SA(b, h) + aoff + m * 2048 + k * 1024); } while (0)
; #define PG8_LDB(dst, b, h) do { _Pragma("unroll") for (int n = 0; n < 2; ++n) _Pragma("unroll") for (int k = 0; k < 2; ++k) dst[n][k] = *(const PG8_LAS bf16x8*)(lds + PG8_SB(b, h) + boff + n * 2048 + k * 1024); } while (0)
; #define PG8_MMA(ai, bj, At, Bt) do { __builtin_amdgcn_s_setprio(1); _Pragma("unroll") for (int m = 0; m < 4; ++m) _Pragma("unroll") for (int n = 0; n < 2; ++n) _Pragma("unroll") for (int k = 0; k < 2; ++k) \
;         acc[ai][bj][m][n] = __builtin_amdgcn_mfma_f32_16x16x32_bf16(Bt[n][k], At[m][k], acc[ai][bj][m][n], 0, 0, 0); __builtin_amdgcn_s_setprio(0); } while (0)
; #define PG8_WAIT_V(n) asm volatile("s_waitcnt vmcnt(" #n ")" ::: "memory")
; #define PG8_WAIT_L(n) asm volatile("s_waitcnt lgkmcnt(" #n ")" ::: "memory")
; #define PG8_BAR __builtin_amdgcn_s_barrier()
; template <class Epi, class Sched, bool ALIGN_EPI = true>
; __device__ __forceinline__ void gemm_phase(PG8_LAS unsigned char* lds, const Gemm g, const Sched& S, const Epi& E, const int tid) {
;     ...
;             const bool last = (t == nt - 2);
;             const char* a1 = cA + (size_t)(t + 1) * kstep;
;             const char* a2 = last ? nA : cA + (size_t)(t + 2) * kstep; const char* b2 = last ? nB : cB + (size_t)(t + 2) * kstep;
;             const char* a3 = a2 + kstep; const char* b3 = b2 + kstep;
;             if (last && has_next) S.a_ready(nxt);
;             PG8_LDB(B0, 0, 0); PG8_LDB(B1, 0, 1); PG8_SCHED; PG8_LDA(At, 0, 0); PG8_STAGE(PG8_SA(1, 1), a1 + hstepA, voffA);
;             PG8_WAIT_V(8); PG8_WAIT_L(0); PG8_BAR; PG8_MMA(0, 0, At, B0); PG8_MMA(0, 1, At, B1); PG8_BAR; PG8_SCHED;
;             PG8_LDA(At, 0, 1); PG8_STAGE(PG8_SB(0, 0), b2, voffB); PG8_STAGE(PG8_SB(0, 1), b2 + hstepB, voffB); PG8_STAGE(PG8_SA(0, 0), a2, voffA);
;             PG8_WAIT_V(8); PG8_WAIT_L(0); PG8_BAR; PG8_MMA(1, 0, At, B0); PG8_MMA(1, 1, At, B1); PG8_BAR; PG8_SCHED;
.LBB0_1238:
	s_add_u32 s15, s74, 0xfff80080
	s_addc_u32 s16, s75, -1
	s_add_i32 s17, 0, 0x10000
	s_cmp_eq_u32 s21, 28
	s_cselect_b32 s79, s8, s16
	s_cselect_b32 s78, s11, s15
	s_cselect_b32 s77, s13, s20
	s_cselect_b32 s76, s18, s19
	s_add_i32 s15, 0, 0x14000
	v_add_u32_e32 v88, s17, v193
	v_add_u32_e32 v104, s15, v193
	ds_read_b128 v[72:75], v88
	ds_read_b128 v[76:79], v88 offset:1024
	ds_read_b128 v[84:87], v88 offset:2048
	ds_read_b128 v[88:91], v88 offset:3072
	ds_read_b128 v[92:95], v104
	ds_read_b128 v[96:99], v104 offset:1024
	ds_read_b128 v[100:103], v104 offset:2048
	ds_read_b128 v[104:107], v104 offset:3072
	s_add_i32 m0, s86, 0xc000
	ds_read_b128 v[164:167], v200
	ds_read_b128 v[168:171], v200 offset:1024
	ds_read_b128 v[172:175], v200 offset:2048
	ds_read_b128 v[176:179], v200 offset:3072
	ds_read_b128 v[202:205], v200 offset:4096
	ds_read_b128 v[210:213], v200 offset:5120
	ds_read_b128 v[214:217], v200 offset:6144
	ds_read_b128 v[218:221], v200 offset:7168
	global_load_lds_dwordx4 v186, s[74:75]
	s_add_i32 m0, s86, 0xe000
	s_nop 0
	global_load_lds_dwordx4 v188, s[74:75]
	s_waitcnt vmcnt(8)
	s_waitcnt lgkmcnt(0)
	s_barrier
	v_mfma_f32_16x16x32_bf16 v[160:163], v[72:75], v[164:167], v[160:163]
	v_mfma_f32_16x16x32_bf16 v[160:163], v[76:79], v[168:171], v[160:163]
	v_mfma_f32_16x16x32_bf16 v[156:159], v[88:91], v[168:171], v[156:159]
	v_mfma_f32_16x16x32_bf16 v[156:159], v[84:87], v[164:167], v[156:159]
	v_mfma_f32_16x16x32_bf16 v[140:143], v[84:87], v[172:175], v[140:143]
	v_mfma_f32_16x16x32_bf16 v[140:143], v[88:91], v[176:179], v[140:143]
	v_mfma_f32_16x16x32_bf16 v[144:147], v[76:79], v[176:179], v[144:147]
	v_mfma_f32_16x16x32_bf16 v[144:147], v[72:75], v[172:175], v[144:147]
	v_mfma_f32_16x16x32_bf16 v[128:131], v[72:75], v[202:205], v[128:131]
	v_mfma_f32_16x16x32_bf16 v[128:131], v[76:79], v[210:213], v[128:131]
	v_mfma_f32_16x16x32_bf16 v[124:127], v[88:91], v[210:213], v[124:127]
	v_mfma_f32_16x16x32_bf16 v[124:127], v[84:87], v[202:205], v[124:127]
	v_mfma_f32_16x16x32_bf16 v[68:71], v[84:87], v[214:217], v[68:71]
	v_mfma_f32_16x16x32_bf16 v[68:71], v[88:91], v[218:221], v[68:71]
	v_mfma_f32_16x16x32_bf16 v[80:83], v[76:79], v[218:221], v[80:83]
	v_mfma_f32_16x16x32_bf16 v[80:83], v[72:75], v[214:217], v[80:83]
	v_mfma_f32_16x16x32_bf16 v[152:155], v[92:95], v[164:167], v[152:155]
	v_mfma_f32_16x16x32_bf16 v[152:155], v[96:99], v[168:171], v[152:155]
	v_mfma_f32_16x16x32_bf16 v[148:151], v[104:107], v[168:171], v[148:151]
	v_mfma_f32_16x16x32_bf16 v[148:151], v[100:103], v[164:167], v[148:151]
	v_mfma_f32_16x16x32_bf16 v[132:135], v[100:103], v[172:175], v[132:135]
	v_mfma_f32_16x16x32_bf16 v[132:135], v[104:107], v[176:179], v[132:135]
	v_mfma_f32_16x16x32_bf16 v[136:139], v[96:99], v[176:179], v[136:139]
	v_mfma_f32_16x16x32_bf16 v[136:139], v[92:95], v[172:175], v[136:139]
	v_mfma_f32_16x16x32_bf16 v[120:123], v[92:95], v[202:205], v[120:123]
	v_mfma_f32_16x16x32_bf16 v[120:123], v[96:99], v[210:213], v[120:123]
	v_mfma_f32_16x16x32_bf16 v[116:119], v[104:107], v[210:213], v[116:119]
	v_mfma_f32_16x16x32_bf16 v[116:119], v[100:103], v[202:205], v[116:119]
	v_mfma_f32_16x16x32_bf16 v[108:111], v[100:103], v[214:217], v[108:111]
	v_mfma_f32_16x16x32_bf16 v[108:111], v[104:107], v[218:221], v[108:111]
	v_mfma_f32_16x16x32_bf16 v[112:115], v[96:99], v[218:221], v[112:115]
	v_mfma_f32_16x16x32_bf16 v[112:115], v[92:95], v[214:217], v[112:115]
	s_barrier
	s_add_i32 s16, s17, s85
	s_mov_b32 m0, s16
	ds_read_b128 v[164:167], v200 offset:16384
	ds_read_b128 v[168:171], v200 offset:17408
	ds_read_b128 v[172:175], v200 offset:18432
	ds_read_b128 v[176:179], v200 offset:19456
	ds_read_b128 v[202:205], v200 offset:20480
	ds_read_b128 v[210:213], v200 offset:21504
	ds_read_b128 v[214:217], v200 offset:22528
	ds_read_b128 v[218:221], v200 offset:23552
	global_load_lds_dwordx4 v2, s[76:77]
	s_add_i32 m0, s16, 0x2000
	s_add_u32 s96, s76, 0x80000
	s_addc_u32 s97, s77, 0
	s_add_i32 s15, s15, s85
	global_load_lds_dwordx4 v184, s[76:77]
	s_mov_b32 m0, s15
	s_nop 0
	global_load_lds_dwordx4 v2, s[96:97]
	s_add_i32 m0, s15, 0x2000
	s_nop 0
	global_load_lds_dwordx4 v184, s[96:97]
	s_mov_b32 m0, s86
	s_nop 0
	global_load_lds_dwordx4 v180, s[78:79]
	s_mov_b32 m0, s87
	s_nop 0
	global_load_lds_dwordx4 v182, s[78:79]
	s_waitcnt vmcnt(8)
	s_waitcnt lgkmcnt(0)
	s_barrier
	v_mfma_f32_16x16x32_bf16 v[64:67], v[72:75], v[164:167], v[64:67]
	v_mfma_f32_16x16x32_bf16 v[64:67], v[76:79], v[168:171], v[64:67]
	v_mfma_f32_16x16x32_bf16 v[60:63], v[88:91], v[168:171], v[60:63]
	v_mfma_f32_16x16x32_bf16 v[60:63], v[84:87], v[164:167], v[60:63]
	v_mfma_f32_16x16x32_bf16 v[44:47], v[84:87], v[172:175], v[44:47]
	v_mfma_f32_16x16x32_bf16 v[44:47], v[88:91], v[176:179], v[44:47]
	v_mfma_f32_16x16x32_bf16 v[48:51], v[76:79], v[176:179], v[48:51]
	v_mfma_f32_16x16x32_bf16 v[48:51], v[72:75], v[172:175], v[48:51]
	v_mfma_f32_16x16x32_bf16 v[32:35], v[72:75], v[202:205], v[32:35]
	v_mfma_f32_16x16x32_bf16 v[32:35], v[76:79], v[210:213], v[32:35]
	v_mfma_f32_16x16x32_bf16 v[28:31], v[88:91], v[210:213], v[28:31]
	v_mfma_f32_16x16x32_bf16 v[28:31], v[84:87], v[202:205], v[28:31]
	v_mfma_f32_16x16x32_bf16 v[4:7], v[84:87], v[214:217], v[4:7]
	v_mfma_f32_16x16x32_bf16 v[4:7], v[88:91], v[218:221], v[4:7]
	v_mfma_f32_16x16x32_bf16 v[8:11], v[76:79], v[218:221], v[8:11]
	v_mfma_f32_16x16x32_bf16 v[8:11], v[72:75], v[214:217], v[8:11]
	v_mfma_f32_16x16x32_bf16 v[56:59], v[92:95], v[164:167], v[56:59]
	v_mfma_f32_16x16x32_bf16 v[56:59], v[96:99], v[168:171], v[56:59]
	v_mfma_f32_16x16x32_bf16 v[52:55], v[104:107], v[168:171], v[52:55]
	v_mfma_f32_16x16x32_bf16 v[52:55], v[100:103], v[164:167], v[52:55]
	v_mfma_f32_16x16x32_bf16 v[36:39], v[100:103], v[172:175], v[36:39]
	v_mfma_f32_16x16x32_bf16 v[36:39], v[104:107], v[176:179], v[36:39]
	v_mfma_f32_16x16x32_bf16 v[40:43], v[96:99], v[176:179], v[40:43]
	v_mfma_f32_16x16x32_bf16 v[40:43], v[92:95], v[172:175], v[40:43]
	v_mfma_f32_16x16x32_bf16 v[24:27], v[92:95], v[202:205], v[24:27]
	v_mfma_f32_16x16x32_bf16 v[24:27], v[96:99], v[210:213], v[24:27]
	v_mfma_f32_16x16x32_bf16 v[20:23], v[104:107], v[210:213], v[20:23]
	v_mfma_f32_16x16x32_bf16 v[20:23], v[100:103], v[202:205], v[20:23]
	v_mfma_f32_16x16x32_bf16 v[12:15], v[100:103], v[214:217], v[12:15]
	v_mfma_f32_16x16x32_bf16 v[12:15], v[104:107], v[218:221], v[12:15]
	v_mfma_f32_16x16x32_bf16 v[16:19], v[96:99], v[218:221], v[16:19]
	v_mfma_f32_16x16x32_bf16 v[16:19], v[92:95], v[214:217], v[16:19]
	s_barrier
; #define PG8_STAGE(bufoff, gbase, voff) do { _Pragma("unroll") for (int _i = 0; _i < 2; ++_i) \
;         __builtin_amdgcn_global_load_lds((const unsigned*)((const char*)(gbase) + (voff)[_i]), (PG8_LAS unsigned*)(lds + (bufoff) + ldsw + _i * 8192), 16, 0, 0); } while (0)
; #define PG8_LDA(dst, b, h) do { _Pragma("unroll") for (int m = 0; m < 4; ++m) _Pragma("unroll") for (int k = 0; k < 2; ++k) dst[m][k] = *(const PG8_LAS bf16x8*)(lds + PG8_SA(b, h) + aoff + m * 2048 + k * 1024); } while (0)
; #define PG8_LDB(dst, b, h) do { _Pragma("unroll") for (int n = 0; n < 2; ++n) _Pragma("unroll") for (int k = 0; k < 2; ++k) dst[n][k] = *(const PG8_LAS bf16x8*)(lds + PG8_SB(b, h) + boff + n * 2048 + k * 1024); } while (0)
; #define PG8_MMA(ai, bj, At, Bt) do { __builtin_amdgcn_s_setprio(1); _Pragma("unroll") for (int m = 0; m < 4; ++m) _Pragma("unroll") for (int n = 0; n < 2; ++n) _Pragma("unroll") for (int k = 0; k < 2; ++k) \
;         acc[ai][bj][m][n] = __builtin_amdgcn_mfma_f32_16x16x32_bf16(Bt[n][k], At[m][k], acc[ai][bj][m][n], 0, 0, 0); __builtin_amdgcn_s_setprio(0); } while (0)
; #define PG8_WAIT_V(n) asm volatile("s_waitcnt vmcnt(" #n ")" ::: "memory")
; #define PG8_WAIT_L(n) asm volatile("s_waitcnt lgkmcnt(" #n ")" ::: "memory")
; #define PG8_BAR __builtin_amdgcn_s_barrier()
; #define PG8_SCHED __builtin_amdgcn_sched_barrier(0)
; template <class Epi, class Sched, bool ALIGN_EPI = true>
; __device__ __forceinline__ void gemm_phase(PG8_LAS unsigned char* lds, const Gemm g, const Sched& S, const Epi& E, const int tid) {
;     ...
;             PG8_LDB(B0, 1, 0); PG8_LDB(B1, 1, 1); PG8_SCHED; PG8_LDA(At, 1, 0); PG8_STAGE(PG8_SA(0, 1), a2 + hstepA, voffA);
;             PG8_WAIT_V(8); PG8_WAIT_L(0); PG8_BAR; PG8_MMA(0, 0, At, B0); PG8_MMA(0, 1, At, B1); PG8_BAR; PG8_SCHED;
;             PG8_LDA(At, 1, 1); PG8_STAGE(PG8_SB(1, 0), b3, voffB); PG8_STAGE(PG8_SB(1, 1), b3 + hstepB, voffB); PG8_STAGE(PG8_SA(1, 0), a3, voffA);
;             PG8_WAIT_V(8); PG8_WAIT_L(0); PG8_BAR; PG8_MMA(1, 0, At, B0); PG8_MMA(1, 1, At, B1); PG8_BAR; PG8_SCHED;
;         }
	s_add_i32 s15, 0, 0x18000
	s_add_i32 s16, 0, 0x1c000
	v_add_u32_e32 v88, s15, v193
	v_add_u32_e32 v104, s16, v193
	ds_read_b128 v[72:75], v88
	ds_read_b128 v[76:79], v88 offset:1024
	ds_read_b128 v[84:87], v88 offset:2048
	ds_read_b128 v[88:91], v88 offset:3072
	ds_read_b128 v[92:95], v104
	ds_read_b128 v[96:99], v104 offset:1024
	ds_read_b128 v[100:103], v104 offset:2048
	ds_read_b128 v[104:107], v104 offset:3072
	s_add_u32 s78, s78, 0x80000
	s_addc_u32 s79, s79, 0
	s_mov_b32 m0, s88
	ds_read_b128 v[164:167], v200 offset:32768
	ds_read_b128 v[168:171], v200 offset:33792
	ds_read_b128 v[172:175], v200 offset:34816
	ds_read_b128 v[176:179], v200 offset:35840
	ds_read_b128 v[202:205], v200 offset:36864
	ds_read_b128 v[210:213], v200 offset:37888
	ds_read_b128 v[214:217], v200 offset:38912
	ds_read_b128 v[218:221], v200 offset:39936
	global_load_lds_dwordx4 v180, s[78:79]
	s_mov_b32 m0, s89
	s_nop 0
	global_load_lds_dwordx4 v182, s[78:79]
	s_waitcnt vmcnt(8)
	s_waitcnt lgkmcnt(0)
	s_barrier
	v_mfma_f32_16x16x32_bf16 v[160:163], v[72:75], v[164:167], v[160:163]
	v_mfma_f32_16x16x32_bf16 v[160:163], v[76:79], v[168:171], v[160:163]
	v_mfma_f32_16x16x32_bf16 v[156:159], v[88:91], v[168:171], v[156:159]
	v_mfma_f32_16x16x32_bf16 v[156:159], v[84:87], v[164:167], v[156:159]
	v_mfma_f32_16x16x32_bf16 v[140:143], v[84:87], v[172:175], v[140:143]
	v_mfma_f32_16x16x32_bf16 v[140:143], v[88:91], v[176:179], v[140:143]
	v_mfma_f32_16x16x32_bf16 v[144:147], v[76:79], v[176:179], v[144:147]
	v_mfma_f32_16x16x32_bf16 v[144:147], v[72:75], v[172:175], v[144:147]
	v_mfma_f32_16x16x32_bf16 v[128:131], v[72:75], v[202:205], v[128:131]
	v_mfma_f32_16x16x32_bf16 v[128:131], v[76:79], v[210:213], v[128:131]
	v_mfma_f32_16x16x32_bf16 v[124:127], v[88:91], v[210:213], v[124:127]
	v_mfma_f32_16x16x32_bf16 v[124:127], v[84:87], v[202:205], v[124:127]
	v_mfma_f32_16x16x32_bf16 v[68:71], v[84:87], v[214:217], v[68:71]
	v_mfma_f32_16x16x32_bf16 v[68:71], v[88:91], v[218:221], v[68:71]
	v_mfma_f32_16x16x32_bf16 v[80:83], v[76:79], v[218:221], v[80:83]
	v_mfma_f32_16x16x32_bf16 v[80:83], v[72:75], v[214:217], v[80:83]
	v_mfma_f32_16x16x32_bf16 v[152:155], v[92:95], v[164:167], v[152:155]
	v_mfma_f32_16x16x32_bf16 v[152:155], v[96:99], v[168:171], v[152:155]
	v_mfma_f32_16x16x32_bf16 v[148:151], v[104:107], v[168:171], v[148:151]
	v_mfma_f32_16x16x32_bf16 v[148:151], v[100:103], v[164:167], v[148:151]
	v_mfma_f32_16x16x32_bf16 v[132:135], v[100:103], v[172:175], v[132:135]
	v_mfma_f32_16x16x32_bf16 v[132:135], v[104:107], v[176:179], v[132:135]
	v_mfma_f32_16x16x32_bf16 v[136:139], v[96:99], v[176:179], v[136:139]
	v_mfma_f32_16x16x32_bf16 v[136:139], v[92:95], v[172:175], v[136:139]
	v_mfma_f32_16x16x32_bf16 v[120:123], v[92:95], v[202:205], v[120:123]
	v_mfma_f32_16x16x32_bf16 v[120:123], v[96:99], v[210:213], v[120:123]
	v_mfma_f32_16x16x32_bf16 v[116:119], v[104:107], v[210:213], v[116:119]
	v_mfma_f32_16x16x32_bf16 v[116:119], v[100:103], v[202:205], v[116:119]
	v_mfma_f32_16x16x32_bf16 v[108:111], v[100:103], v[214:217], v[108:111]
	v_mfma_f32_16x16x32_bf16 v[108:111], v[104:107], v[218:221], v[108:111]
	v_mfma_f32_16x16x32_bf16 v[112:115], v[96:99], v[218:221], v[112:115]
	v_mfma_f32_16x16x32_bf16 v[112:115], v[92:95], v[214:217], v[112:115]
	s_barrier
	s_add_i32 s15, s15, s85
	s_mov_b32 m0, s15
	ds_read_b128 v[164:167], v200 offset:49152
	ds_read_b128 v[168:171], v200 offset:50176
	ds_read_b128 v[172:175], v200 offset:51200
	ds_read_b128 v[176:179], v200 offset:52224
	ds_read_b128 v[202:205], v200 offset:53248
	ds_read_b128 v[210:213], v200 offset:54272
	ds_read_b128 v[214:217], v200 offset:55296
	ds_read_b128 v[218:221], v200 offset:56320
	s_add_u32 s98, s76, 0x80
	s_addc_u32 s99, s77, 0
	global_load_lds_dwordx4 v2, s[98:99]
	s_add_i32 m0, s15, 0x2000
	s_add_u32 s76, s76, 0x80080
	s_addc_u32 s77, s77, 0
	s_add_i32 s15, s16, s85
	global_load_lds_dwordx4 v184, s[98:99]
	s_mov_b32 m0, s15
	s_nop 0
	global_load_lds_dwordx4 v2, s[76:77]
	s_add_i32 m0, s15, 0x2000
	s_nop 0
	global_load_lds_dwordx4 v184, s[76:77]
	s_mov_b32 m0, s92
	s_nop 0
	s_add_u32 s98, s78, 0xfff80080
	s_addc_u32 s99, s79, -1
	global_load_lds_dwordx4 v180, s[98:99]
	s_mov_b32 m0, s93
	s_nop 0
	global_load_lds_dwordx4 v182, s[98:99]
	s_waitcnt vmcnt(8)
	s_waitcnt lgkmcnt(0)
	s_barrier
	v_mfma_f32_16x16x32_bf16 v[64:67], v[72:75], v[164:167], v[64:67]
	v_mfma_f32_16x16x32_bf16 v[64:67], v[76:79], v[168:171], v[64:67]
	v_mfma_f32_16x16x32_bf16 v[60:63], v[88:91], v[168:171], v[60:63]
	v_mfma_f32_16x16x32_bf16 v[60:63], v[84:87], v[164:167], v[60:63]
	v_mfma_f32_16x16x32_bf16 v[44:47], v[84:87], v[172:175], v[44:47]
	v_mfma_f32_16x16x32_bf16 v[44:47], v[88:91], v[176:179], v[44:47]
	v_mfma_f32_16x16x32_bf16 v[48:51], v[76:79], v[176:179], v[48:51]
	v_mfma_f32_16x16x32_bf16 v[48:51], v[72:75], v[172:175], v[48:51]
	v_mfma_f32_16x16x32_bf16 v[32:35], v[72:75], v[202:205], v[32:35]
	v_mfma_f32_16x16x32_bf16 v[32:35], v[76:79], v[210:213], v[32:35]
	v_mfma_f32_16x16x32_bf16 v[28:31], v[88:91], v[210:213], v[28:31]
	v_mfma_f32_16x16x32_bf16 v[28:31], v[84:87], v[202:205], v[28:31]
	v_mfma_f32_16x16x32_bf16 v[4:7], v[84:87], v[214:217], v[4:7]
	v_mfma_f32_16x16x32_bf16 v[4:7], v[88:91], v[218:221], v[4:7]
	v_mfma_f32_16x16x32_bf16 v[8:11], v[76:79], v[218:221], v[8:11]
	v_mfma_f32_16x16x32_bf16 v[8:11], v[72:75], v[214:217], v[8:11]
	v_mfma_f32_16x16x32_bf16 v[56:59], v[92:95], v[164:167], v[56:59]
	v_mfma_f32_16x16x32_bf16 v[56:59], v[96:99], v[168:171], v[56:59]
	v_mfma_f32_16x16x32_bf16 v[52:55], v[104:107], v[168:171], v[52:55]
	v_mfma_f32_16x16x32_bf16 v[52:55], v[100:103], v[164:167], v[52:55]
	v_mfma_f32_16x16x32_bf16 v[36:39], v[100:103], v[172:175], v[36:39]
	v_mfma_f32_16x16x32_bf16 v[36:39], v[104:107], v[176:179], v[36:39]
	v_mfma_f32_16x16x32_bf16 v[40:43], v[96:99], v[176:179], v[40:43]
	v_mfma_f32_16x16x32_bf16 v[40:43], v[92:95], v[172:175], v[40:43]
	v_mfma_f32_16x16x32_bf16 v[24:27], v[92:95], v[202:205], v[24:27]
	v_mfma_f32_16x16x32_bf16 v[24:27], v[96:99], v[210:213], v[24:27]
	v_mfma_f32_16x16x32_bf16 v[20:23], v[104:107], v[210:213], v[20:23]
	v_mfma_f32_16x16x32_bf16 v[20:23], v[100:103], v[202:205], v[20:23]
	v_mfma_f32_16x16x32_bf16 v[12:15], v[100:103], v[214:217], v[12:15]
	v_mfma_f32_16x16x32_bf16 v[12:15], v[104:107], v[218:221], v[12:15]
	v_mfma_f32_16x16x32_bf16 v[16:19], v[96:99], v[218:221], v[16:19]
	v_mfma_f32_16x16x32_bf16 v[16:19], v[92:95], v[214:217], v[16:19]
	s_barrier
	s_add_i32 s21, s21, 2
	s_add_u32 s74, s74, 0x100
	s_addc_u32 s75, s75, 0
	s_add_u32 s19, s19, 0x100
	s_addc_u32 s20, s20, 0
	s_cmp_gt_u32 s21, 29
	s_cbranch_scc0 .LBB0_1238
	s_and_b64 vcc, exec, s[56:57]
	s_cbranch_vccnz .LBB0_1264
	s_and_saveexec_b64 s[18:19], s[38:39]
	s_cbranch_execnz .LBB0_1265

; #define PG8_STAGE(bufoff, gbase, voff) do { _Pragma("unroll") for (int _i = 0; _i < 2; ++_i) \
;         __builtin_amdgcn_global_load_lds((const unsigned*)((const char*)(gbase) + (voff)[_i]), (PG8_LAS unsigned*)(lds + (bufoff) + ldsw + _i * 8192), 16, 0, 0); } while (0)
; #define PG8_LDA(dst, b, h) do { _Pragma("unroll") for (int m = 0; m < 4; ++m) _Pragma("unroll") for (int k = 0; k < 2; ++k) dst[m][k] = *(const PG8_LAS bf16x8*)(lds + PG8_SA(b, h) + aoff + m * 2048 + k * 1024); } while (0)
; #define PG8_LDB(dst, b, h) do { _Pragma("unroll") for (int n = 0; n < 2; ++n) _Pragma("unroll") for (int k = 0; k < 2; ++k) dst[n][k] = *(const PG8_LAS bf16x8*)(lds + PG8_SB(b, h) + boff + n * 2048 + k * 1024); } while (0)
; #define PG8_MMA(ai, bj, At, Bt) do { __builtin_amdgcn_s_setprio(1); _Pragma("unroll") for (int m = 0; m < 4; ++m) _Pragma("unroll") for (int n = 0; n < 2; ++n) _Pragma("unroll") for (int k = 0; k < 2; ++k) \
;         acc[ai][bj][m][n] = __builtin_amdgcn_mfma_f32_16x16x32_bf16(Bt[n][k], At[m][k], acc[ai][bj][m][n], 0, 0, 0); __builtin_amdgcn_s_setprio(0); } while (0)
; #define PG8_WAIT_V(n) asm volatile("s_waitcnt vmcnt(" #n ")" ::: "memory")
; #define PG8_WAIT_L(n) asm volatile("s_waitcnt lgkmcnt(" #n ")" ::: "memory")
; #define PG8_BAR __builtin_amdgcn_s_barrier()
; template <class Epi, class Sched, bool ALIGN_EPI = true>
; __device__ __forceinline__ void gemm_phase(PG8_LAS unsigned char* lds, const Gemm g, const Sched& S, const Epi& E, const int tid) {
;     ...
;             const bool last = (t == nt - 2);
;             const char* a1 = cA + (size_t)(t + 1) * kstep;
;             const char* a2 = last ? nA : cA + (size_t)(t + 2) * kstep; const char* b2 = last ? nB : cB + (size_t)(t + 2) * kstep;
;             const char* a3 = a2 + kstep; const char* b3 = b2 + kstep;
;             if (last && has_next) S.a_ready(nxt);
;             PG8_LDB(B0, 0, 0); PG8_LDB(B1, 0, 1); PG8_SCHED; PG8_LDA(At, 0, 0); PG8_STAGE(PG8_SA(1, 1), a1 + hstepA, voffA);
;             PG8_WAIT_V(8); PG8_WAIT_L(0); PG8_BAR; PG8_MMA(0, 0, At, B0); PG8_MMA(0, 1, At, B1); PG8_BAR; PG8_SCHED;
;             PG8_LDA(At, 0, 1); PG8_STAGE(PG8_SB(0, 0), b2, voffB); PG8_STAGE(PG8_SB(0, 1), b2 + hstepB, voffB); PG8_STAGE(PG8_SA(0, 0), a2, voffA);
;             PG8_WAIT_V(8); PG8_WAIT_L(0); PG8_BAR; PG8_MMA(1, 0, At, B0); PG8_MMA(1, 1, At, B1); PG8_BAR; PG8_SCHED;
.LBB0_1414:
	s_add_i32 s70, s12, 2
	s_add_u32 s10, s0, 0x100
	s_addc_u32 s11, s1, 0
	s_add_i32 s15, 0, 0x10000
	s_cmp_eq_u32 s45, s12
	s_cselect_b32 s23, s47, s11
	s_cselect_b32 s22, s46, s10
	s_cselect_b32 s13, s49, s69
	s_cselect_b32 s12, s48, s68
	s_add_i32 s16, 0, 0x14000
	v_add_u32_e32 v72, s15, v251
	v_add_u32_e32 v128, s16, v251
	ds_read_b128 v[56:59], v72
	ds_read_b128 v[60:63], v72 offset:1024
	ds_read_b128 v[68:71], v72 offset:2048
	ds_read_b128 v[72:75], v72 offset:3072
	ds_read_b128 v[92:95], v128
	ds_read_b128 v[104:107], v128 offset:1024
	ds_read_b128 v[116:119], v128 offset:2048
	ds_read_b128 v[128:131], v128 offset:3072
	s_add_i32 m0, s52, 0xc000
	ds_read_b128 v[140:143], v252
	ds_read_b128 v[152:155], v252 offset:1024
	ds_read_b128 v[156:159], v252 offset:2048
	ds_read_b128 v[160:163], v252 offset:3072
	ds_read_b128 v[172:175], v252 offset:4096
	ds_read_b128 v[184:187], v252 offset:5120
	ds_read_b128 v[188:191], v252 offset:6144
	ds_read_b128 v[192:195], v252 offset:7168
	global_load_lds_dwordx4 v216, s[0:1]
	s_add_i32 m0, s52, 0xe000
	s_nop 0
	global_load_lds_dwordx4 v218, s[0:1]
	s_waitcnt vmcnt(8)
	s_waitcnt lgkmcnt(0)
	s_barrier
	v_mfma_f32_16x16x32_bf16 v[180:183], v[56:59], v[140:143], v[180:183]
	v_mfma_f32_16x16x32_bf16 v[180:183], v[60:63], v[152:155], v[180:183]
	v_mfma_f32_16x16x32_bf16 v[176:179], v[72:75], v[152:155], v[176:179]
	v_mfma_f32_16x16x32_bf16 v[176:179], v[68:71], v[140:143], v[176:179]
	v_mfma_f32_16x16x32_bf16 v[144:147], v[68:71], v[156:159], v[144:147]
	v_mfma_f32_16x16x32_bf16 v[144:147], v[72:75], v[160:163], v[144:147]
	v_mfma_f32_16x16x32_bf16 v[148:151], v[60:63], v[160:163], v[148:151]
	v_mfma_f32_16x16x32_bf16 v[148:151], v[56:59], v[156:159], v[148:151]
	v_mfma_f32_16x16x32_bf16 v[124:127], v[56:59], v[172:175], v[124:127]
	v_mfma_f32_16x16x32_bf16 v[124:127], v[60:63], v[184:187], v[124:127]
	v_mfma_f32_16x16x32_bf16 v[120:123], v[72:75], v[184:187], v[120:123]
	v_mfma_f32_16x16x32_bf16 v[120:123], v[68:71], v[172:175], v[120:123]
	v_mfma_f32_16x16x32_bf16 v[96:99], v[68:71], v[188:191], v[96:99]
	v_mfma_f32_16x16x32_bf16 v[96:99], v[72:75], v[192:195], v[96:99]
	v_mfma_f32_16x16x32_bf16 v[100:103], v[60:63], v[192:195], v[100:103]
	v_mfma_f32_16x16x32_bf16 v[100:103], v[56:59], v[188:191], v[100:103]
	v_mfma_f32_16x16x32_bf16 v[168:171], v[92:95], v[140:143], v[168:171]
	v_mfma_f32_16x16x32_bf16 v[168:171], v[104:107], v[152:155], v[168:171]
	v_mfma_f32_16x16x32_bf16 v[136:139], v[104:107], v[160:163], v[136:139]
	v_mfma_f32_16x16x32_bf16 v[136:139], v[92:95], v[156:159], v[136:139]
	v_mfma_f32_16x16x32_bf16 v[132:135], v[116:119], v[156:159], v[132:135]
	v_mfma_f32_16x16x32_bf16 v[132:135], v[128:131], v[160:163], v[132:135]
	v_mfma_f32_16x16x32_bf16 v[108:111], v[128:131], v[184:187], v[108:111]
	v_mfma_f32_16x16x32_bf16 v[108:111], v[116:119], v[172:175], v[108:111]
	v_mfma_f32_16x16x32_bf16 v[112:115], v[92:95], v[172:175], v[112:115]
	v_mfma_f32_16x16x32_bf16 v[112:115], v[104:107], v[184:187], v[112:115]
	v_mfma_f32_16x16x32_bf16 v[88:91], v[104:107], v[192:195], v[88:91]
	v_mfma_f32_16x16x32_bf16 v[88:91], v[92:95], v[188:191], v[88:91]
	v_mfma_f32_16x16x32_bf16 v[84:87], v[116:119], v[188:191], v[84:87]
	v_mfma_f32_16x16x32_bf16 v[84:87], v[128:131], v[192:195], v[84:87]
	v_mfma_f32_16x16x32_bf16 v[140:143], v[116:119], v[140:143], v[164:167]
	v_mfma_f32_16x16x32_bf16 v[140:143], v[128:131], v[152:155], v[140:143]
	s_barrier
	s_add_i32 s0, s15, s51
	s_mov_b32 m0, s0
	ds_read_b128 v[152:155], v252 offset:16384
	ds_read_b128 v[156:159], v252 offset:17408
	ds_read_b128 v[160:163], v252 offset:18432
	ds_read_b128 v[164:167], v252 offset:19456
	ds_read_b128 v[172:175], v252 offset:20480
	ds_read_b128 v[184:187], v252 offset:21504
	ds_read_b128 v[188:191], v252 offset:22528
	ds_read_b128 v[192:195], v252 offset:23552
	global_load_lds_dwordx4 v2, s[12:13]
	s_add_i32 m0, s0, 0x2000
	s_add_u32 s0, s12, 0x168000
	s_addc_u32 s1, s13, 0
	s_add_i32 s15, s16, s51
	global_load_lds_dwordx4 v214, s[12:13]
	s_mov_b32 m0, s15
	s_nop 0
	global_load_lds_dwordx4 v2, s[0:1]
	s_add_i32 m0, s15, 0x2000
	s_nop 0
	global_load_lds_dwordx4 v214, s[0:1]
	s_mov_b32 m0, s52
	s_nop 0
	global_load_lds_dwordx4 v210, s[22:23]
	s_mov_b32 m0, s53
	s_nop 0
	global_load_lds_dwordx4 v212, s[22:23]
	s_waitcnt vmcnt(8)
	s_waitcnt lgkmcnt(0)
	s_barrier
	v_mfma_f32_16x16x32_bf16 v[80:83], v[56:59], v[152:155], v[80:83]
	v_mfma_f32_16x16x32_bf16 v[80:83], v[60:63], v[156:159], v[80:83]
	v_mfma_f32_16x16x32_bf16 v[76:79], v[72:75], v[156:159], v[76:79]
	v_mfma_f32_16x16x32_bf16 v[76:79], v[68:71], v[152:155], v[76:79]
	v_mfma_f32_16x16x32_bf16 v[44:47], v[68:71], v[160:163], v[44:47]
	v_mfma_f32_16x16x32_bf16 v[44:47], v[72:75], v[164:167], v[44:47]
	v_mfma_f32_16x16x32_bf16 v[48:51], v[60:63], v[164:167], v[48:51]
	v_mfma_f32_16x16x32_bf16 v[48:51], v[56:59], v[160:163], v[48:51]
	v_mfma_f32_16x16x32_bf16 v[32:35], v[56:59], v[172:175], v[32:35]
	v_mfma_f32_16x16x32_bf16 v[32:35], v[60:63], v[184:187], v[32:35]
	v_mfma_f32_16x16x32_bf16 v[28:31], v[72:75], v[184:187], v[28:31]
	v_mfma_f32_16x16x32_bf16 v[28:31], v[68:71], v[172:175], v[28:31]
	v_mfma_f32_16x16x32_bf16 v[12:15], v[68:71], v[188:191], v[12:15]
	v_mfma_f32_16x16x32_bf16 v[12:15], v[72:75], v[192:195], v[12:15]
	v_mfma_f32_16x16x32_bf16 v[16:19], v[60:63], v[192:195], v[16:19]
	v_mfma_f32_16x16x32_bf16 v[16:19], v[56:59], v[188:191], v[16:19]
	v_mfma_f32_16x16x32_bf16 v[52:55], v[116:119], v[152:155], v[52:55]
	v_mfma_f32_16x16x32_bf16 v[52:55], v[128:131], v[156:159], v[52:55]
	v_mfma_f32_16x16x32_bf16 v[36:39], v[128:131], v[164:167], v[36:39]
	v_mfma_f32_16x16x32_bf16 v[36:39], v[116:119], v[160:163], v[36:39]
	v_mfma_f32_16x16x32_bf16 v[40:43], v[92:95], v[160:163], v[40:43]
	v_mfma_f32_16x16x32_bf16 v[40:43], v[104:107], v[164:167], v[40:43]
	v_mfma_f32_16x16x32_bf16 v[24:27], v[104:107], v[184:187], v[24:27]
	v_mfma_f32_16x16x32_bf16 v[24:27], v[92:95], v[172:175], v[24:27]
	v_mfma_f32_16x16x32_bf16 v[20:23], v[116:119], v[172:175], v[20:23]
	v_mfma_f32_16x16x32_bf16 v[20:23], v[128:131], v[184:187], v[20:23]
	v_mfma_f32_16x16x32_bf16 v[4:7], v[128:131], v[192:195], v[4:7]
	v_mfma_f32_16x16x32_bf16 v[4:7], v[116:119], v[188:191], v[4:7]
	v_mfma_f32_16x16x32_bf16 v[8:11], v[92:95], v[188:191], v[8:11]
	v_mfma_f32_16x16x32_bf16 v[8:11], v[104:107], v[192:195], v[8:11]
	v_mfma_f32_16x16x32_bf16 v[56:59], v[92:95], v[152:155], v[64:67]
	v_mfma_f32_16x16x32_bf16 v[56:59], v[104:107], v[156:159], v[56:59]
	s_barrier
; #define PG8_STAGE(bufoff, gbase, voff) do { _Pragma("unroll") for (int _i = 0; _i < 2; ++_i) \
;         __builtin_amdgcn_global_load_lds((const unsigned*)((const char*)(gbase) + (voff)[_i]), (PG8_LAS unsigned*)(lds + (bufoff) + ldsw + _i * 8192), 16, 0, 0); } while (0)
; #define PG8_LDA(dst, b, h) do { _Pragma("unroll") for (int m = 0; m < 4; ++m) _Pragma("unroll") for (int k = 0; k < 2; ++k) dst[m][k] = *(const PG8_LAS bf16x8*)(lds + PG8_SA(b, h) + aoff + m * 2048 + k * 1024); } while (0)
; #define PG8_LDB(dst, b, h) do { _Pragma("unroll") for (int n = 0; n < 2; ++n) _Pragma("unroll") for (int k = 0; k < 2; ++k) dst[n][k] = *(const PG8_LAS bf16x8*)(lds + PG8_SB(b, h) + boff + n * 2048 + k * 1024); } while (0)
; #define PG8_MMA(ai, bj, At, Bt) do { __builtin_amdgcn_s_setprio(1); _Pragma("unroll") for (int m = 0; m < 4; ++m) _Pragma("unroll") for (int n = 0; n < 2; ++n) _Pragma("unroll") for (int k = 0; k < 2; ++k) \
;         acc[ai][bj][m][n] = __builtin_amdgcn_mfma_f32_16x16x32_bf16(Bt[n][k], At[m][k], acc[ai][bj][m][n], 0, 0, 0); __builtin_amdgcn_s_setprio(0); } while (0)
; #define PG8_WAIT_V(n) asm volatile("s_waitcnt vmcnt(" #n ")" ::: "memory")
; #define PG8_WAIT_L(n) asm volatile("s_waitcnt lgkmcnt(" #n ")" ::: "memory")
; #define PG8_BAR __builtin_amdgcn_s_barrier()
; #define PG8_SCHED __builtin_amdgcn_sched_barrier(0)
; template <class Epi, class Sched, bool ALIGN_EPI = true>
; __device__ __forceinline__ void gemm_phase(PG8_LAS unsigned char* lds, const Gemm g, const Sched& S, const Epi& E, const int tid) {
;     ...
;             PG8_LDB(B0, 1, 0); PG8_LDB(B1, 1, 1); PG8_SCHED; PG8_LDA(At, 1, 0); PG8_STAGE(PG8_SA(0, 1), a2 + hstepA, voffA);
;             PG8_WAIT_V(8); PG8_WAIT_L(0); PG8_BAR; PG8_MMA(0, 0, At, B0); PG8_MMA(0, 1, At, B1); PG8_BAR; PG8_SCHED;
;             PG8_LDA(At, 1, 1); PG8_STAGE(PG8_SB(1, 0), b3, voffB); PG8_STAGE(PG8_SB(1, 1), b3 + hstepB, voffB); PG8_STAGE(PG8_SA(1, 0), a3, voffA);
;             PG8_WAIT_V(8); PG8_WAIT_L(0); PG8_BAR; PG8_MMA(1, 0, At, B0); PG8_MMA(1, 1, At, B1); PG8_BAR; PG8_SCHED;
;         }
;         if constexpr (ALIGN_EPI) { if (wr == 0) PG8_BAR; }
	s_add_i32 s15, 0, 0x18000
	s_add_i32 s16, 0, 0x1c000
	v_add_u32_e32 v72, s15, v251
	v_add_u32_e32 v128, s16, v251
	ds_read_b128 v[60:63], v72
	ds_read_b128 v[64:67], v72 offset:1024
	ds_read_b128 v[68:71], v72 offset:2048
	ds_read_b128 v[72:75], v72 offset:3072
	ds_read_b128 v[92:95], v128
	ds_read_b128 v[104:107], v128 offset:1024
	ds_read_b128 v[116:119], v128 offset:2048
	ds_read_b128 v[128:131], v128 offset:3072
	s_add_u32 s0, s22, 0x168000
	s_addc_u32 s1, s23, 0
	s_mov_b32 m0, s54
	ds_read_b128 v[152:155], v252 offset:32768
	ds_read_b128 v[156:159], v252 offset:33792
	ds_read_b128 v[160:163], v252 offset:34816
	ds_read_b128 v[172:175], v252 offset:35840
	ds_read_b128 v[184:187], v252 offset:36864
	ds_read_b128 v[188:191], v252 offset:37888
	ds_read_b128 v[192:195], v252 offset:38912
	ds_read_b128 v[196:199], v252 offset:39936
	global_load_lds_dwordx4 v210, s[0:1]
	s_mov_b32 m0, s55
	s_nop 0
	global_load_lds_dwordx4 v212, s[0:1]
	s_waitcnt vmcnt(8)
	s_waitcnt lgkmcnt(0)
	s_barrier
	v_mfma_f32_16x16x32_bf16 v[164:167], v[60:63], v[152:155], v[180:183]
	v_mfma_f32_16x16x32_bf16 v[180:183], v[64:67], v[156:159], v[164:167]
	v_mfma_f32_16x16x32_bf16 v[148:151], v[64:67], v[172:175], v[148:151]
	v_mfma_f32_16x16x32_bf16 v[148:151], v[60:63], v[160:163], v[148:151]
	v_mfma_f32_16x16x32_bf16 v[144:147], v[68:71], v[160:163], v[144:147]
	v_mfma_f32_16x16x32_bf16 v[144:147], v[72:75], v[172:175], v[144:147]
	v_mfma_f32_16x16x32_bf16 v[120:123], v[72:75], v[188:191], v[120:123]
	v_mfma_f32_16x16x32_bf16 v[120:123], v[68:71], v[184:187], v[120:123]
	v_mfma_f32_16x16x32_bf16 v[164:167], v[68:71], v[152:155], v[176:179]
	v_mfma_f32_16x16x32_bf16 v[176:179], v[72:75], v[156:159], v[164:167]
	v_mfma_f32_16x16x32_bf16 v[96:99], v[72:75], v[196:199], v[96:99]
	v_mfma_f32_16x16x32_bf16 v[96:99], v[68:71], v[192:195], v[96:99]
	v_mfma_f32_16x16x32_bf16 v[100:103], v[60:63], v[192:195], v[100:103]
	v_mfma_f32_16x16x32_bf16 v[100:103], v[64:67], v[196:199], v[100:103]
	v_mfma_f32_16x16x32_bf16 v[124:127], v[64:67], v[188:191], v[124:127]
	v_mfma_f32_16x16x32_bf16 v[124:127], v[60:63], v[184:187], v[124:127]
	v_mfma_f32_16x16x32_bf16 v[164:167], v[92:95], v[152:155], v[168:171]
	v_mfma_f32_16x16x32_bf16 v[168:171], v[104:107], v[156:159], v[164:167]
	v_mfma_f32_16x16x32_bf16 v[136:139], v[104:107], v[172:175], v[136:139]
	v_mfma_f32_16x16x32_bf16 v[136:139], v[92:95], v[160:163], v[136:139]
	v_mfma_f32_16x16x32_bf16 v[132:135], v[116:119], v[160:163], v[132:135]
	v_mfma_f32_16x16x32_bf16 v[132:135], v[128:131], v[172:175], v[132:135]
	v_mfma_f32_16x16x32_bf16 v[108:111], v[128:131], v[188:191], v[108:111]
	v_mfma_f32_16x16x32_bf16 v[108:111], v[116:119], v[184:187], v[108:111]
	v_mfma_f32_16x16x32_bf16 v[140:143], v[116:119], v[152:155], v[140:143]
	v_mfma_f32_16x16x32_bf16 v[164:167], v[128:131], v[156:159], v[140:143]
	v_mfma_f32_16x16x32_bf16 v[84:87], v[128:131], v[196:199], v[84:87]
	v_mfma_f32_16x16x32_bf16 v[84:87], v[116:119], v[192:195], v[84:87]
	v_mfma_f32_16x16x32_bf16 v[88:91], v[92:95], v[192:195], v[88:91]
	v_mfma_f32_16x16x32_bf16 v[88:91], v[104:107], v[196:199], v[88:91]
	v_mfma_f32_16x16x32_bf16 v[112:115], v[104:107], v[188:191], v[112:115]
	v_mfma_f32_16x16x32_bf16 v[112:115], v[92:95], v[184:187], v[112:115]
	s_barrier
	s_add_i32 s0, s15, s51
	s_mov_b32 m0, s0
	ds_read_b128 v[140:143], v252 offset:49152
	ds_read_b128 v[152:155], v252 offset:50176
	ds_read_b128 v[156:159], v252 offset:51200
	ds_read_b128 v[160:163], v252 offset:52224
	ds_read_b128 v[172:175], v252 offset:53248
	ds_read_b128 v[184:187], v252 offset:54272
	ds_read_b128 v[188:191], v252 offset:55296
	ds_read_b128 v[192:195], v252 offset:56320
	s_add_u32 s98, s12, 0x80
	s_addc_u32 s99, s13, 0
	global_load_lds_dwordx4 v2, s[98:99]
	s_add_i32 m0, s0, 0x2000
	s_add_u32 s0, s12, 0x168080
	s_addc_u32 s1, s13, 0
	s_add_i32 s12, s16, s51
	global_load_lds_dwordx4 v214, s[98:99]
	s_mov_b32 m0, s12
	s_nop 0
	global_load_lds_dwordx4 v2, s[0:1]
	s_add_i32 m0, s12, 0x2000
	s_nop 0
	global_load_lds_dwordx4 v214, s[0:1]
	s_mov_b32 m0, s58
	s_nop 0
	s_add_u32 s98, s22, 0x80
	s_addc_u32 s99, s23, 0
	global_load_lds_dwordx4 v210, s[98:99]
	s_mov_b32 m0, s59
	s_nop 0
	global_load_lds_dwordx4 v212, s[98:99]
	s_waitcnt vmcnt(8)
	s_waitcnt lgkmcnt(0)
	s_barrier
	v_mfma_f32_16x16x32_bf16 v[80:83], v[60:63], v[140:143], v[80:83]
	v_mfma_f32_16x16x32_bf16 v[80:83], v[64:67], v[152:155], v[80:83]
	v_mfma_f32_16x16x32_bf16 v[76:79], v[72:75], v[152:155], v[76:79]
	v_mfma_f32_16x16x32_bf16 v[76:79], v[68:71], v[140:143], v[76:79]
	v_mfma_f32_16x16x32_bf16 v[44:47], v[68:71], v[156:159], v[44:47]
	v_mfma_f32_16x16x32_bf16 v[44:47], v[72:75], v[160:163], v[44:47]
	v_mfma_f32_16x16x32_bf16 v[48:51], v[64:67], v[160:163], v[48:51]
	v_mfma_f32_16x16x32_bf16 v[48:51], v[60:63], v[156:159], v[48:51]
	v_mfma_f32_16x16x32_bf16 v[32:35], v[60:63], v[172:175], v[32:35]
	v_mfma_f32_16x16x32_bf16 v[32:35], v[64:67], v[184:187], v[32:35]
	v_mfma_f32_16x16x32_bf16 v[28:31], v[72:75], v[184:187], v[28:31]
	v_mfma_f32_16x16x32_bf16 v[28:31], v[68:71], v[172:175], v[28:31]
	v_mfma_f32_16x16x32_bf16 v[12:15], v[68:71], v[188:191], v[12:15]
	v_mfma_f32_16x16x32_bf16 v[12:15], v[72:75], v[192:195], v[12:15]
	v_mfma_f32_16x16x32_bf16 v[16:19], v[64:67], v[192:195], v[16:19]
	v_mfma_f32_16x16x32_bf16 v[16:19], v[60:63], v[188:191], v[16:19]
	v_mfma_f32_16x16x32_bf16 v[56:59], v[92:95], v[140:143], v[56:59]
	v_mfma_f32_16x16x32_bf16 v[64:67], v[104:107], v[152:155], v[56:59]
	v_mfma_f32_16x16x32_bf16 v[52:55], v[128:131], v[152:155], v[52:55]
	v_mfma_f32_16x16x32_bf16 v[52:55], v[116:119], v[140:143], v[52:55]
	v_mfma_f32_16x16x32_bf16 v[36:39], v[116:119], v[156:159], v[36:39]
	v_mfma_f32_16x16x32_bf16 v[36:39], v[128:131], v[160:163], v[36:39]
	v_mfma_f32_16x16x32_bf16 v[40:43], v[104:107], v[160:163], v[40:43]
	v_mfma_f32_16x16x32_bf16 v[40:43], v[92:95], v[156:159], v[40:43]
	v_mfma_f32_16x16x32_bf16 v[24:27], v[92:95], v[172:175], v[24:27]
	v_mfma_f32_16x16x32_bf16 v[24:27], v[104:107], v[184:187], v[24:27]
	v_mfma_f32_16x16x32_bf16 v[20:23], v[128:131], v[184:187], v[20:23]
	v_mfma_f32_16x16x32_bf16 v[20:23], v[116:119], v[172:175], v[20:23]
	v_mfma_f32_16x16x32_bf16 v[4:7], v[116:119], v[188:191], v[4:7]
	v_mfma_f32_16x16x32_bf16 v[4:7], v[128:131], v[192:195], v[4:7]
	v_mfma_f32_16x16x32_bf16 v[8:11], v[104:107], v[192:195], v[8:11]
	v_mfma_f32_16x16x32_bf16 v[8:11], v[92:95], v[188:191], v[8:11]
	s_barrier
	s_add_u32 s68, s68, 0x100
	s_addc_u32 s69, s69, 0
	s_cmp_ge_i32 s70, s67
	s_mov_b64 s[0:1], s[10:11]
	s_mov_b32 s12, s70
	s_cbranch_scc0 .LBB0_1414
	s_nop 0
	s_nop 0
	s_nop 0
	s_nop 0
	s_nop 0
	s_nop 0
	s_nop 0
	s_nop 0
	s_nop 0
	s_nop 0
	s_nop 0
	s_nop 0
	s_and_b64 vcc, exec, s[42:43]
	s_cbranch_vccz .LBB0_1417
	s_barrier
